# barrier trims + mid-MMA s_setprio 0/1 pair removed (one prio-1 run of 32 MFMAs per phase)
# speedup vs baseline: 1.0136x; 1.0032x over previous
.LBB0_262:
	s_add_i32 vcc_lo, s38, 2
	s_add_u32 s39, s10, 0xfff00080
	s_addc_u32 s66, s11, -1
	s_add_i32 s67, 0, 0x10000
	s_cmp_eq_u32 s35, s38
	s_cselect_b32 s87, s53, s66
	s_cselect_b32 s86, s52, s39
	s_cselect_b32 s39, s13, s49
	s_cselect_b32 s38, s15, s40
	s_add_i32 vcc_hi, 0, 0x14000
	v_add_u32_e32 v142, s67, v1
	v_add_u32_e32 v180, vcc_hi, v1
	ds_read_b128 v[130:133], v142
	ds_read_b128 v[134:137], v142 offset:1024
	ds_read_b128 v[138:141], v142 offset:2048
	ds_read_b128 v[142:145], v142 offset:3072
	ds_read_b128 v[168:171], v180
	ds_read_b128 v[172:175], v180 offset:1024
	ds_read_b128 v[176:179], v180 offset:2048
	ds_read_b128 v[180:183], v180 offset:3072
	v_lshl_add_u64 v[184:185], s[10:11], 0, v[164:165]
	s_add_i32 m0, s85, 0xc000
	ds_read_b128 v[198:201], v197
	ds_read_b128 v[202:205], v197 offset:1024
	ds_read_b128 v[206:209], v197 offset:2048
	ds_read_b128 v[210:213], v197 offset:3072
	ds_read_b128 v[214:217], v197 offset:4096
	ds_read_b128 v[218:221], v197 offset:5120
	ds_read_b128 v[222:225], v197 offset:6144
	ds_read_b128 v[226:229], v197 offset:7168
	global_load_lds_dwordx4 v[184:185], off
	v_lshl_add_u64 v[184:185], s[10:11], 0, v[166:167]
	s_add_i32 m0, s85, 0xe000
	s_nop 0
	global_load_lds_dwordx4 v[184:185], off
	s_waitcnt vmcnt(8)
	s_waitcnt lgkmcnt(0)
	s_setprio 1
	s_barrier
	v_mfma_f32_16x16x32_bf16 v[114:117], v[130:133], v[198:201], v[114:117]
	v_mfma_f32_16x16x32_bf16 v[118:121], v[138:141], v[198:201], v[118:121]
	v_mfma_f32_16x16x32_bf16 v[102:105], v[130:133], v[206:209], v[102:105]
	v_mfma_f32_16x16x32_bf16 v[98:101], v[138:141], v[206:209], v[98:101]
	v_mfma_f32_16x16x32_bf16 v[86:89], v[130:133], v[214:217], v[86:89]
	v_mfma_f32_16x16x32_bf16 v[82:85], v[138:141], v[214:217], v[82:85]
	v_mfma_f32_16x16x32_bf16 v[54:57], v[130:133], v[222:225], v[54:57]
	v_mfma_f32_16x16x32_bf16 v[50:53], v[138:141], v[222:225], v[50:53]
	v_mfma_f32_16x16x32_bf16 v[114:117], v[134:137], v[202:205], v[114:117]
	v_mfma_f32_16x16x32_bf16 v[118:121], v[142:145], v[202:205], v[118:121]
	v_mfma_f32_16x16x32_bf16 v[102:105], v[134:137], v[210:213], v[102:105]
	v_mfma_f32_16x16x32_bf16 v[98:101], v[142:145], v[210:213], v[98:101]
	v_mfma_f32_16x16x32_bf16 v[86:89], v[134:137], v[218:221], v[86:89]
	v_mfma_f32_16x16x32_bf16 v[82:85], v[142:145], v[218:221], v[82:85]
	v_mfma_f32_16x16x32_bf16 v[54:57], v[134:137], v[226:229], v[54:57]
	v_mfma_f32_16x16x32_bf16 v[50:53], v[142:145], v[226:229], v[50:53]
	v_mfma_f32_16x16x32_bf16 v[126:129], v[168:171], v[198:201], v[126:129]
	v_mfma_f32_16x16x32_bf16 v[122:125], v[176:179], v[198:201], v[122:125]
	v_mfma_f32_16x16x32_bf16 v[110:113], v[168:171], v[206:209], v[110:113]
	v_mfma_f32_16x16x32_bf16 v[106:109], v[176:179], v[206:209], v[106:109]
	v_mfma_f32_16x16x32_bf16 v[94:97], v[168:171], v[214:217], v[94:97]
	v_mfma_f32_16x16x32_bf16 v[90:93], v[176:179], v[214:217], v[90:93]
	v_mfma_f32_16x16x32_bf16 v[70:73], v[168:171], v[222:225], v[70:73]
	v_mfma_f32_16x16x32_bf16 v[66:69], v[176:179], v[222:225], v[66:69]
	v_mfma_f32_16x16x32_bf16 v[126:129], v[172:175], v[202:205], v[126:129]
	v_mfma_f32_16x16x32_bf16 v[122:125], v[180:183], v[202:205], v[122:125]
	v_mfma_f32_16x16x32_bf16 v[110:113], v[172:175], v[210:213], v[110:113]
	v_mfma_f32_16x16x32_bf16 v[106:109], v[180:183], v[210:213], v[106:109]
	v_mfma_f32_16x16x32_bf16 v[94:97], v[172:175], v[218:221], v[94:97]
	v_mfma_f32_16x16x32_bf16 v[90:93], v[180:183], v[218:221], v[90:93]
	v_mfma_f32_16x16x32_bf16 v[70:73], v[172:175], v[226:229], v[70:73]
	v_mfma_f32_16x16x32_bf16 v[66:69], v[180:183], v[226:229], v[66:69]
	s_barrier
	s_setprio 0
	s_add_i32 s66, s67, s97
	v_lshl_add_u64 v[184:185], s[38:39], 0, v[156:157]
	s_mov_b32 m0, s66
	ds_read_b128 v[198:201], v197 offset:16384
	ds_read_b128 v[202:205], v197 offset:17408
	ds_read_b128 v[206:209], v197 offset:18432
	ds_read_b128 v[210:213], v197 offset:19456
	ds_read_b128 v[214:217], v197 offset:20480
	ds_read_b128 v[218:221], v197 offset:21504
	ds_read_b128 v[222:225], v197 offset:22528
	ds_read_b128 v[226:229], v197 offset:23552
	global_load_lds_dwordx4 v[184:185], off
	s_add_i32 m0, s66, 0x2000
	s_add_u32 s66, s38, 0x100000
	v_lshl_add_u64 v[230:231], s[38:39], 0, v[160:161]
	s_addc_u32 s67, s39, 0
	s_add_i32 vcc_hi, vcc_hi, s97
	global_load_lds_dwordx4 v[230:231], off
	v_lshl_add_u64 v[232:233], s[66:67], 0, v[156:157]
	s_mov_b32 m0, vcc_hi
	v_lshl_add_u64 v[234:235], s[86:87], 0, v[158:159]
	global_load_lds_dwordx4 v[232:233], off
	v_lshl_add_u64 v[232:233], s[66:67], 0, v[160:161]
	s_add_i32 m0, vcc_hi, 0x2000
	s_nop 0
	global_load_lds_dwordx4 v[232:233], off
	v_lshl_add_u64 v[232:233], s[86:87], 0, v[154:155]
	s_mov_b32 m0, s85
	s_nop 0
	global_load_lds_dwordx4 v[232:233], off
	s_mov_b32 m0, s92
	s_nop 0
	global_load_lds_dwordx4 v[234:235], off
	s_waitcnt vmcnt(8)
	s_waitcnt lgkmcnt(0)
	s_setprio 1
	s_barrier
	v_mfma_f32_16x16x32_bf16 v[62:65], v[130:133], v[198:201], v[62:65]
	v_mfma_f32_16x16x32_bf16 v[58:61], v[138:141], v[198:201], v[58:61]
	v_mfma_f32_16x16x32_bf16 v[38:41], v[130:133], v[206:209], v[38:41]
	v_mfma_f32_16x16x32_bf16 v[34:37], v[138:141], v[206:209], v[34:37]
	v_mfma_f32_16x16x32_bf16 v[22:25], v[130:133], v[214:217], v[22:25]
	v_mfma_f32_16x16x32_bf16 v[18:21], v[138:141], v[214:217], v[18:21]
	v_mfma_f32_16x16x32_bf16 v[6:9], v[130:133], v[222:225], v[6:9]
	v_mfma_f32_16x16x32_bf16 v[2:5], v[138:141], v[222:225], v[2:5]
	v_mfma_f32_16x16x32_bf16 v[62:65], v[134:137], v[202:205], v[62:65]
	v_mfma_f32_16x16x32_bf16 v[58:61], v[142:145], v[202:205], v[58:61]
	v_mfma_f32_16x16x32_bf16 v[38:41], v[134:137], v[210:213], v[38:41]
	v_mfma_f32_16x16x32_bf16 v[34:37], v[142:145], v[210:213], v[34:37]
	v_mfma_f32_16x16x32_bf16 v[22:25], v[134:137], v[218:221], v[22:25]
	v_mfma_f32_16x16x32_bf16 v[18:21], v[142:145], v[218:221], v[18:21]
	v_mfma_f32_16x16x32_bf16 v[6:9], v[134:137], v[226:229], v[6:9]
	v_mfma_f32_16x16x32_bf16 v[2:5], v[142:145], v[226:229], v[2:5]
	v_mfma_f32_16x16x32_bf16 v[78:81], v[168:171], v[198:201], v[78:81]
	v_mfma_f32_16x16x32_bf16 v[74:77], v[176:179], v[198:201], v[74:77]
	v_mfma_f32_16x16x32_bf16 v[46:49], v[168:171], v[206:209], v[46:49]
	v_mfma_f32_16x16x32_bf16 v[42:45], v[176:179], v[206:209], v[42:45]
	v_mfma_f32_16x16x32_bf16 v[30:33], v[168:171], v[214:217], v[30:33]
	v_mfma_f32_16x16x32_bf16 v[26:29], v[176:179], v[214:217], v[26:29]
	v_mfma_f32_16x16x32_bf16 v[14:17], v[168:171], v[222:225], v[14:17]
	v_mfma_f32_16x16x32_bf16 v[10:13], v[176:179], v[222:225], v[10:13]
	v_mfma_f32_16x16x32_bf16 v[78:81], v[172:175], v[202:205], v[78:81]
	v_mfma_f32_16x16x32_bf16 v[74:77], v[180:183], v[202:205], v[74:77]
	v_mfma_f32_16x16x32_bf16 v[46:49], v[172:175], v[210:213], v[46:49]
	v_mfma_f32_16x16x32_bf16 v[42:45], v[180:183], v[210:213], v[42:45]
	v_mfma_f32_16x16x32_bf16 v[30:33], v[172:175], v[218:221], v[30:33]
	v_mfma_f32_16x16x32_bf16 v[26:29], v[180:183], v[218:221], v[26:29]
	v_mfma_f32_16x16x32_bf16 v[14:17], v[172:175], v[226:229], v[14:17]
	v_mfma_f32_16x16x32_bf16 v[10:13], v[180:183], v[226:229], v[10:13]
	s_barrier
	s_setprio 0
	s_add_i32 vcc_hi, 0, 0x18000
	s_add_i32 s56, 0, 0x1c000
	v_add_u32_e32 v142, vcc_hi, v1
	v_add_u32_e32 v180, s56, v1
	ds_read_b128 v[130:133], v142
	ds_read_b128 v[134:137], v142 offset:1024
	ds_read_b128 v[138:141], v142 offset:2048
	ds_read_b128 v[142:145], v142 offset:3072
	ds_read_b128 v[168:171], v180
	ds_read_b128 v[172:175], v180 offset:1024
	ds_read_b128 v[176:179], v180 offset:2048
	ds_read_b128 v[180:183], v180 offset:3072
	s_add_u32 s66, s86, 0x100000
	s_addc_u32 s67, s87, 0
	s_mov_b32 m0, s93
	v_lshl_add_u64 v[236:237], s[66:67], 0, v[154:155]
	ds_read_b128 v[198:201], v197 offset:32768
	ds_read_b128 v[202:205], v197 offset:33792
	ds_read_b128 v[206:209], v197 offset:34816
	ds_read_b128 v[210:213], v197 offset:35840
	ds_read_b128 v[214:217], v197 offset:36864
	ds_read_b128 v[218:221], v197 offset:37888
	ds_read_b128 v[222:225], v197 offset:38912
	ds_read_b128 v[226:229], v197 offset:39936
	global_load_lds_dwordx4 v[236:237], off
	v_lshl_add_u64 v[236:237], s[66:67], 0, v[158:159]
	s_mov_b32 m0, s42
	s_nop 0
	global_load_lds_dwordx4 v[236:237], off
	s_waitcnt vmcnt(8)
	s_waitcnt lgkmcnt(0)
	s_setprio 1
	s_barrier
	v_mfma_f32_16x16x32_bf16 v[114:117], v[130:133], v[198:201], v[114:117]
	v_mfma_f32_16x16x32_bf16 v[118:121], v[138:141], v[198:201], v[118:121]
	v_mfma_f32_16x16x32_bf16 v[102:105], v[130:133], v[206:209], v[102:105]
	v_mfma_f32_16x16x32_bf16 v[98:101], v[138:141], v[206:209], v[98:101]
	v_mfma_f32_16x16x32_bf16 v[86:89], v[130:133], v[214:217], v[86:89]
	v_mfma_f32_16x16x32_bf16 v[82:85], v[138:141], v[214:217], v[82:85]
	v_mfma_f32_16x16x32_bf16 v[54:57], v[130:133], v[222:225], v[54:57]
	v_mfma_f32_16x16x32_bf16 v[50:53], v[138:141], v[222:225], v[50:53]
	v_mfma_f32_16x16x32_bf16 v[114:117], v[134:137], v[202:205], v[114:117]
	v_mfma_f32_16x16x32_bf16 v[118:121], v[142:145], v[202:205], v[118:121]
	v_mfma_f32_16x16x32_bf16 v[102:105], v[134:137], v[210:213], v[102:105]
	v_mfma_f32_16x16x32_bf16 v[98:101], v[142:145], v[210:213], v[98:101]
	v_mfma_f32_16x16x32_bf16 v[86:89], v[134:137], v[218:221], v[86:89]
	v_mfma_f32_16x16x32_bf16 v[82:85], v[142:145], v[218:221], v[82:85]
	v_mfma_f32_16x16x32_bf16 v[54:57], v[134:137], v[226:229], v[54:57]
	v_mfma_f32_16x16x32_bf16 v[50:53], v[142:145], v[226:229], v[50:53]
	v_mfma_f32_16x16x32_bf16 v[126:129], v[168:171], v[198:201], v[126:129]
	v_mfma_f32_16x16x32_bf16 v[122:125], v[176:179], v[198:201], v[122:125]
	v_mfma_f32_16x16x32_bf16 v[110:113], v[168:171], v[206:209], v[110:113]
	v_mfma_f32_16x16x32_bf16 v[106:109], v[176:179], v[206:209], v[106:109]
	v_mfma_f32_16x16x32_bf16 v[94:97], v[168:171], v[214:217], v[94:97]
	v_mfma_f32_16x16x32_bf16 v[90:93], v[176:179], v[214:217], v[90:93]
	v_mfma_f32_16x16x32_bf16 v[70:73], v[168:171], v[222:225], v[70:73]
	v_mfma_f32_16x16x32_bf16 v[66:69], v[176:179], v[222:225], v[66:69]
	v_mfma_f32_16x16x32_bf16 v[126:129], v[172:175], v[202:205], v[126:129]
	v_mfma_f32_16x16x32_bf16 v[122:125], v[180:183], v[202:205], v[122:125]
	v_mfma_f32_16x16x32_bf16 v[110:113], v[172:175], v[210:213], v[110:113]
	v_mfma_f32_16x16x32_bf16 v[106:109], v[180:183], v[210:213], v[106:109]
	v_mfma_f32_16x16x32_bf16 v[94:97], v[172:175], v[218:221], v[94:97]
	v_mfma_f32_16x16x32_bf16 v[90:93], v[180:183], v[218:221], v[90:93]
	v_mfma_f32_16x16x32_bf16 v[70:73], v[172:175], v[226:229], v[70:73]
	v_mfma_f32_16x16x32_bf16 v[66:69], v[180:183], v[226:229], v[66:69]
	s_barrier
	s_setprio 0
	s_add_i32 s57, vcc_hi, s97
	v_lshl_add_u64 v[184:185], v[184:185], 0, s[94:95]
	s_mov_b32 m0, s57
	ds_read_b128 v[198:201], v197 offset:49152
	ds_read_b128 v[202:205], v197 offset:50176
	ds_read_b128 v[206:209], v197 offset:51200
	ds_read_b128 v[210:213], v197 offset:52224
	ds_read_b128 v[214:217], v197 offset:53248
	ds_read_b128 v[218:221], v197 offset:54272
	ds_read_b128 v[222:225], v197 offset:55296
	ds_read_b128 v[226:229], v197 offset:56320
	global_load_lds_dwordx4 v[184:185], off
	s_add_i32 m0, s57, 0x2000
	s_add_u32 s38, s38, 0x100080
	v_lshl_add_u64 v[184:185], v[230:231], 0, s[94:95]
	s_addc_u32 s39, s39, 0
	s_add_i32 s56, s56, s97
	global_load_lds_dwordx4 v[184:185], off
	v_lshl_add_u64 v[184:185], s[38:39], 0, v[156:157]
	s_mov_b32 m0, s56
	s_nop 0
	global_load_lds_dwordx4 v[184:185], off
	v_lshl_add_u64 v[184:185], s[38:39], 0, v[160:161]
	s_add_i32 m0, s56, 0x2000
	s_nop 0
	global_load_lds_dwordx4 v[184:185], off
	v_lshl_add_u64 v[184:185], v[232:233], 0, s[94:95]
	s_mov_b32 m0, s43
	s_nop 0
	global_load_lds_dwordx4 v[184:185], off
	v_lshl_add_u64 v[184:185], v[234:235], 0, s[94:95]
	s_mov_b32 m0, s90
	s_nop 0
	global_load_lds_dwordx4 v[184:185], off
	s_waitcnt vmcnt(8)
	s_waitcnt lgkmcnt(0)
	s_setprio 1
	s_barrier
	v_mfma_f32_16x16x32_bf16 v[62:65], v[130:133], v[198:201], v[62:65]
	v_mfma_f32_16x16x32_bf16 v[58:61], v[138:141], v[198:201], v[58:61]
	v_mfma_f32_16x16x32_bf16 v[38:41], v[130:133], v[206:209], v[38:41]
	v_mfma_f32_16x16x32_bf16 v[34:37], v[138:141], v[206:209], v[34:37]
	v_mfma_f32_16x16x32_bf16 v[22:25], v[130:133], v[214:217], v[22:25]
	v_mfma_f32_16x16x32_bf16 v[18:21], v[138:141], v[214:217], v[18:21]
	v_mfma_f32_16x16x32_bf16 v[6:9], v[130:133], v[222:225], v[6:9]
	v_mfma_f32_16x16x32_bf16 v[2:5], v[138:141], v[222:225], v[2:5]
	v_mfma_f32_16x16x32_bf16 v[62:65], v[134:137], v[202:205], v[62:65]
	v_mfma_f32_16x16x32_bf16 v[58:61], v[142:145], v[202:205], v[58:61]
	v_mfma_f32_16x16x32_bf16 v[38:41], v[134:137], v[210:213], v[38:41]
	v_mfma_f32_16x16x32_bf16 v[34:37], v[142:145], v[210:213], v[34:37]
	v_mfma_f32_16x16x32_bf16 v[22:25], v[134:137], v[218:221], v[22:25]
	v_mfma_f32_16x16x32_bf16 v[18:21], v[142:145], v[218:221], v[18:21]
	v_mfma_f32_16x16x32_bf16 v[6:9], v[134:137], v[226:229], v[6:9]
	v_mfma_f32_16x16x32_bf16 v[2:5], v[142:145], v[226:229], v[2:5]
	v_mfma_f32_16x16x32_bf16 v[78:81], v[168:171], v[198:201], v[78:81]
	v_mfma_f32_16x16x32_bf16 v[74:77], v[176:179], v[198:201], v[74:77]
	v_mfma_f32_16x16x32_bf16 v[46:49], v[168:171], v[206:209], v[46:49]
	v_mfma_f32_16x16x32_bf16 v[42:45], v[176:179], v[206:209], v[42:45]
	v_mfma_f32_16x16x32_bf16 v[30:33], v[168:171], v[214:217], v[30:33]
	v_mfma_f32_16x16x32_bf16 v[26:29], v[176:179], v[214:217], v[26:29]
	v_mfma_f32_16x16x32_bf16 v[14:17], v[168:171], v[222:225], v[14:17]
	v_mfma_f32_16x16x32_bf16 v[10:13], v[176:179], v[222:225], v[10:13]
	v_mfma_f32_16x16x32_bf16 v[78:81], v[172:175], v[202:205], v[78:81]
	v_mfma_f32_16x16x32_bf16 v[74:77], v[180:183], v[202:205], v[74:77]
	v_mfma_f32_16x16x32_bf16 v[46:49], v[172:175], v[210:213], v[46:49]
	v_mfma_f32_16x16x32_bf16 v[42:45], v[180:183], v[210:213], v[42:45]
	v_mfma_f32_16x16x32_bf16 v[30:33], v[172:175], v[218:221], v[30:33]
	v_mfma_f32_16x16x32_bf16 v[26:29], v[180:183], v[218:221], v[26:29]
	v_mfma_f32_16x16x32_bf16 v[14:17], v[172:175], v[226:229], v[14:17]
	v_mfma_f32_16x16x32_bf16 v[10:13], v[180:183], v[226:229], v[10:13]
	s_barrier
	s_setprio 0
	s_add_u32 s40, s40, 0x100
	s_addc_u32 s49, s49, 0
	s_add_u32 s10, s10, 0x100
	s_addc_u32 s11, s11, 0
	s_cmp_ge_u32 vcc_lo, s19
	s_mov_b32 s38, vcc_lo
	s_cbranch_scc0 .LBB0_262
	v_readlane_b32 s10, v254, 27
	v_readlane_b32 s11, v254, 28
	s_and_b64 vcc, exec, s[10:11]
	s_cbranch_vccz .LBB0_270
	s_barrier
	s_cmp_lt_i32 s18, 0
	s_mov_b64 s[10:11], -1
	s_cbranch_scc1 .LBB0_271

.LBB0_1693:
	ds_read_b128 v[128:131], v169
	ds_read_b128 v[132:135], v169 offset:1024
	ds_read_b128 v[136:139], v169 offset:2048
	ds_read_b128 v[140:143], v169 offset:3072
	ds_read_b128 v[158:161], v170
	ds_read_b128 v[162:165], v170 offset:1024
	ds_read_b128 v[172:175], v170 offset:2048
	ds_read_b128 v[176:179], v170 offset:3072
	s_add_u32 s24, s22, 0xfff80080
	s_addc_u32 s25, s23, -1
	s_cmp_eq_u32 s36, 4
	s_cselect_b32 s27, s5, s25
	s_cselect_b32 s26, s4, s24
	s_cselect_b32 s25, s13, s35
	s_cselect_b32 s24, s15, s34
	v_lshl_add_u64 v[212:213], s[22:23], 0, v[152:153]
	s_add_i32 m0, s94, 0xc000
	ds_read_b128 v[180:183], v171
	ds_read_b128 v[184:187], v171 offset:1024
	ds_read_b128 v[188:191], v171 offset:2048
	ds_read_b128 v[192:195], v171 offset:3072
	ds_read_b128 v[196:199], v171 offset:4096
	ds_read_b128 v[200:203], v171 offset:5120
	ds_read_b128 v[204:207], v171 offset:6144
	ds_read_b128 v[208:211], v171 offset:7168
	global_load_lds_dwordx4 v[212:213], off
	v_lshl_add_u64 v[212:213], s[22:23], 0, v[154:155]
	s_add_i32 m0, s94, 0xe000
	s_nop 0
	global_load_lds_dwordx4 v[212:213], off
	s_waitcnt vmcnt(8)
	s_waitcnt lgkmcnt(0)
	s_setprio 1
	s_barrier
	v_mfma_f32_16x16x32_bf16 v[80:83], v[128:131], v[180:183], v[80:83]
	v_mfma_f32_16x16x32_bf16 v[92:95], v[136:139], v[180:183], v[92:95]
	v_mfma_f32_16x16x32_bf16 v[84:87], v[128:131], v[188:191], v[84:87]
	v_mfma_f32_16x16x32_bf16 v[96:99], v[136:139], v[188:191], v[96:99]
	v_mfma_f32_16x16x32_bf16 v[88:91], v[128:131], v[196:199], v[88:91]
	v_mfma_f32_16x16x32_bf16 v[100:103], v[136:139], v[196:199], v[100:103]
	v_mfma_f32_16x16x32_bf16 v[72:75], v[128:131], v[204:207], v[72:75]
	v_mfma_f32_16x16x32_bf16 v[76:79], v[136:139], v[204:207], v[76:79]
	v_mfma_f32_16x16x32_bf16 v[80:83], v[132:135], v[184:187], v[80:83]
	v_mfma_f32_16x16x32_bf16 v[92:95], v[140:143], v[184:187], v[92:95]
	v_mfma_f32_16x16x32_bf16 v[84:87], v[132:135], v[192:195], v[84:87]
	v_mfma_f32_16x16x32_bf16 v[96:99], v[140:143], v[192:195], v[96:99]
	v_mfma_f32_16x16x32_bf16 v[88:91], v[132:135], v[200:203], v[88:91]
	v_mfma_f32_16x16x32_bf16 v[100:103], v[140:143], v[200:203], v[100:103]
	v_mfma_f32_16x16x32_bf16 v[72:75], v[132:135], v[208:211], v[72:75]
	v_mfma_f32_16x16x32_bf16 v[76:79], v[140:143], v[208:211], v[76:79]
	v_mfma_f32_16x16x32_bf16 v[104:107], v[158:161], v[180:183], v[104:107]
	v_mfma_f32_16x16x32_bf16 v[116:119], v[172:175], v[180:183], v[116:119]
	v_mfma_f32_16x16x32_bf16 v[108:111], v[158:161], v[188:191], v[108:111]
	v_mfma_f32_16x16x32_bf16 v[120:123], v[172:175], v[188:191], v[120:123]
	v_mfma_f32_16x16x32_bf16 v[112:115], v[158:161], v[196:199], v[112:115]
	v_mfma_f32_16x16x32_bf16 v[124:127], v[172:175], v[196:199], v[124:127]
	v_mfma_f32_16x16x32_bf16 v[68:71], v[158:161], v[204:207], v[68:71]
	v_mfma_f32_16x16x32_bf16 v[64:67], v[172:175], v[204:207], v[64:67]
	v_mfma_f32_16x16x32_bf16 v[104:107], v[162:165], v[184:187], v[104:107]
	v_mfma_f32_16x16x32_bf16 v[116:119], v[176:179], v[184:187], v[116:119]
	v_mfma_f32_16x16x32_bf16 v[108:111], v[162:165], v[192:195], v[108:111]
	v_mfma_f32_16x16x32_bf16 v[120:123], v[176:179], v[192:195], v[120:123]
	v_mfma_f32_16x16x32_bf16 v[112:115], v[162:165], v[200:203], v[112:115]
	v_mfma_f32_16x16x32_bf16 v[124:127], v[176:179], v[200:203], v[124:127]
	v_mfma_f32_16x16x32_bf16 v[68:71], v[162:165], v[208:211], v[68:71]
	v_mfma_f32_16x16x32_bf16 v[64:67], v[176:179], v[208:211], v[64:67]
	s_barrier
	s_setprio 0
	s_add_i32 s37, s31, s97
	v_lshl_add_u64 v[212:213], s[24:25], 0, v[148:149]
	s_mov_b32 m0, s37
	ds_read_b128 v[180:183], v171 offset:16384
	ds_read_b128 v[184:187], v171 offset:17408
	ds_read_b128 v[188:191], v171 offset:18432
	ds_read_b128 v[192:195], v171 offset:19456
	ds_read_b128 v[196:199], v171 offset:20480
	ds_read_b128 v[200:203], v171 offset:21504
	ds_read_b128 v[204:207], v171 offset:22528
	ds_read_b128 v[208:211], v171 offset:23552
	global_load_lds_dwordx4 v[212:213], off
	s_add_i32 m0, s37, 0x2000
	s_add_u32 s38, s24, 0x20000
	v_lshl_add_u64 v[214:215], s[24:25], 0, v[144:145]
	s_addc_u32 s39, s25, 0
	s_add_i32 s37, s33, s97
	global_load_lds_dwordx4 v[214:215], off
	v_lshl_add_u64 v[216:217], s[38:39], 0, v[148:149]
	s_mov_b32 m0, s37
	v_lshl_add_u64 v[218:219], s[26:27], 0, v[146:147]
	global_load_lds_dwordx4 v[216:217], off
	v_lshl_add_u64 v[216:217], s[38:39], 0, v[144:145]
	s_add_i32 m0, s37, 0x2000
	s_nop 0
	global_load_lds_dwordx4 v[216:217], off
	v_lshl_add_u64 v[216:217], s[26:27], 0, v[150:151]
	s_mov_b32 m0, s94
	s_nop 0
	global_load_lds_dwordx4 v[216:217], off
	s_mov_b32 m0, s3
	s_nop 0
	global_load_lds_dwordx4 v[218:219], off
	s_waitcnt vmcnt(8)
	s_waitcnt lgkmcnt(0)
	s_setprio 1
	s_barrier
	v_mfma_f32_16x16x32_bf16 v[48:51], v[128:131], v[180:183], v[48:51]
	v_mfma_f32_16x16x32_bf16 v[52:55], v[136:139], v[180:183], v[52:55]
	v_mfma_f32_16x16x32_bf16 v[32:35], v[128:131], v[188:191], v[32:35]
	v_mfma_f32_16x16x32_bf16 v[36:39], v[136:139], v[188:191], v[36:39]
	v_mfma_f32_16x16x32_bf16 v[16:19], v[128:131], v[196:199], v[16:19]
	v_mfma_f32_16x16x32_bf16 v[20:23], v[136:139], v[196:199], v[20:23]
	v_mfma_f32_16x16x32_bf16 v[0:3], v[128:131], v[204:207], v[0:3]
	v_mfma_f32_16x16x32_bf16 v[4:7], v[136:139], v[204:207], v[4:7]
	v_mfma_f32_16x16x32_bf16 v[48:51], v[132:135], v[184:187], v[48:51]
	v_mfma_f32_16x16x32_bf16 v[52:55], v[140:143], v[184:187], v[52:55]
	v_mfma_f32_16x16x32_bf16 v[32:35], v[132:135], v[192:195], v[32:35]
	v_mfma_f32_16x16x32_bf16 v[36:39], v[140:143], v[192:195], v[36:39]
	v_mfma_f32_16x16x32_bf16 v[16:19], v[132:135], v[200:203], v[16:19]
	v_mfma_f32_16x16x32_bf16 v[20:23], v[140:143], v[200:203], v[20:23]
	v_mfma_f32_16x16x32_bf16 v[0:3], v[132:135], v[208:211], v[0:3]
	v_mfma_f32_16x16x32_bf16 v[4:7], v[140:143], v[208:211], v[4:7]
	v_mfma_f32_16x16x32_bf16 v[56:59], v[158:161], v[180:183], v[56:59]
	v_mfma_f32_16x16x32_bf16 v[60:63], v[172:175], v[180:183], v[60:63]
	v_mfma_f32_16x16x32_bf16 v[40:43], v[158:161], v[188:191], v[40:43]
	v_mfma_f32_16x16x32_bf16 v[44:47], v[172:175], v[188:191], v[44:47]
	v_mfma_f32_16x16x32_bf16 v[24:27], v[158:161], v[196:199], v[24:27]
	v_mfma_f32_16x16x32_bf16 v[28:31], v[172:175], v[196:199], v[28:31]
	v_mfma_f32_16x16x32_bf16 v[8:11], v[158:161], v[204:207], v[8:11]
	v_mfma_f32_16x16x32_bf16 v[12:15], v[172:175], v[204:207], v[12:15]
	v_mfma_f32_16x16x32_bf16 v[56:59], v[162:165], v[184:187], v[56:59]
	v_mfma_f32_16x16x32_bf16 v[60:63], v[176:179], v[184:187], v[60:63]
	v_mfma_f32_16x16x32_bf16 v[40:43], v[162:165], v[192:195], v[40:43]
	v_mfma_f32_16x16x32_bf16 v[44:47], v[176:179], v[192:195], v[44:47]
	v_mfma_f32_16x16x32_bf16 v[24:27], v[162:165], v[200:203], v[24:27]
	v_mfma_f32_16x16x32_bf16 v[28:31], v[176:179], v[200:203], v[28:31]
	v_mfma_f32_16x16x32_bf16 v[8:11], v[162:165], v[208:211], v[8:11]
	v_mfma_f32_16x16x32_bf16 v[12:15], v[176:179], v[208:211], v[12:15]
	s_barrier
	s_setprio 0
	s_add_i32 s37, 0, 0x18000
	s_add_i32 s38, 0, 0x1c000
	v_add_u32_e32 v140, s37, v167
	v_add_u32_e32 v176, s38, v167
	ds_read_b128 v[128:131], v140
	ds_read_b128 v[132:135], v140 offset:1024
	ds_read_b128 v[136:139], v140 offset:2048
	ds_read_b128 v[140:143], v140 offset:3072
	ds_read_b128 v[158:161], v176
	ds_read_b128 v[162:165], v176 offset:1024
	ds_read_b128 v[172:175], v176 offset:2048
	ds_read_b128 v[176:179], v176 offset:3072
	s_add_u32 s26, s26, 0x80000
	s_addc_u32 s27, s27, 0
	s_mov_b32 m0, s7
	v_lshl_add_u64 v[220:221], s[26:27], 0, v[150:151]
	ds_read_b128 v[180:183], v171 offset:32768
	ds_read_b128 v[184:187], v171 offset:33792
	ds_read_b128 v[188:191], v171 offset:34816
	ds_read_b128 v[192:195], v171 offset:35840
	ds_read_b128 v[196:199], v171 offset:36864
	ds_read_b128 v[200:203], v171 offset:37888
	ds_read_b128 v[204:207], v171 offset:38912
	ds_read_b128 v[208:211], v171 offset:39936
	global_load_lds_dwordx4 v[220:221], off
	v_lshl_add_u64 v[220:221], s[26:27], 0, v[146:147]
	s_mov_b32 m0, s19
	s_nop 0
	global_load_lds_dwordx4 v[220:221], off
	s_waitcnt vmcnt(8)
	s_waitcnt lgkmcnt(0)
	s_setprio 1
	s_barrier
	v_mfma_f32_16x16x32_bf16 v[80:83], v[128:131], v[180:183], v[80:83]
	v_mfma_f32_16x16x32_bf16 v[92:95], v[136:139], v[180:183], v[92:95]
	v_mfma_f32_16x16x32_bf16 v[84:87], v[128:131], v[188:191], v[84:87]
	v_mfma_f32_16x16x32_bf16 v[96:99], v[136:139], v[188:191], v[96:99]
	v_mfma_f32_16x16x32_bf16 v[88:91], v[128:131], v[196:199], v[88:91]
	v_mfma_f32_16x16x32_bf16 v[100:103], v[136:139], v[196:199], v[100:103]
	v_mfma_f32_16x16x32_bf16 v[72:75], v[128:131], v[204:207], v[72:75]
	v_mfma_f32_16x16x32_bf16 v[76:79], v[136:139], v[204:207], v[76:79]
	v_mfma_f32_16x16x32_bf16 v[80:83], v[132:135], v[184:187], v[80:83]
	v_mfma_f32_16x16x32_bf16 v[92:95], v[140:143], v[184:187], v[92:95]
	v_mfma_f32_16x16x32_bf16 v[84:87], v[132:135], v[192:195], v[84:87]
	v_mfma_f32_16x16x32_bf16 v[96:99], v[140:143], v[192:195], v[96:99]
	v_mfma_f32_16x16x32_bf16 v[88:91], v[132:135], v[200:203], v[88:91]
	v_mfma_f32_16x16x32_bf16 v[100:103], v[140:143], v[200:203], v[100:103]
	v_mfma_f32_16x16x32_bf16 v[72:75], v[132:135], v[208:211], v[72:75]
	v_mfma_f32_16x16x32_bf16 v[76:79], v[140:143], v[208:211], v[76:79]
	v_mfma_f32_16x16x32_bf16 v[104:107], v[158:161], v[180:183], v[104:107]
	v_mfma_f32_16x16x32_bf16 v[116:119], v[172:175], v[180:183], v[116:119]
	v_mfma_f32_16x16x32_bf16 v[108:111], v[158:161], v[188:191], v[108:111]
	v_mfma_f32_16x16x32_bf16 v[120:123], v[172:175], v[188:191], v[120:123]
	v_mfma_f32_16x16x32_bf16 v[112:115], v[158:161], v[196:199], v[112:115]
	v_mfma_f32_16x16x32_bf16 v[124:127], v[172:175], v[196:199], v[124:127]
	v_mfma_f32_16x16x32_bf16 v[68:71], v[158:161], v[204:207], v[68:71]
	v_mfma_f32_16x16x32_bf16 v[64:67], v[172:175], v[204:207], v[64:67]
	v_mfma_f32_16x16x32_bf16 v[104:107], v[162:165], v[184:187], v[104:107]
	v_mfma_f32_16x16x32_bf16 v[116:119], v[176:179], v[184:187], v[116:119]
	v_mfma_f32_16x16x32_bf16 v[108:111], v[162:165], v[192:195], v[108:111]
	v_mfma_f32_16x16x32_bf16 v[120:123], v[176:179], v[192:195], v[120:123]
	v_mfma_f32_16x16x32_bf16 v[112:115], v[162:165], v[200:203], v[112:115]
	v_mfma_f32_16x16x32_bf16 v[124:127], v[176:179], v[200:203], v[124:127]
	v_mfma_f32_16x16x32_bf16 v[68:71], v[162:165], v[208:211], v[68:71]
	v_mfma_f32_16x16x32_bf16 v[64:67], v[176:179], v[208:211], v[64:67]
	s_barrier
	s_setprio 0
	s_add_i32 s26, s37, s97
	v_lshl_add_u64 v[212:213], v[212:213], 0, s[0:1]
	s_mov_b32 m0, s26
	ds_read_b128 v[180:183], v171 offset:49152
	ds_read_b128 v[184:187], v171 offset:50176
	ds_read_b128 v[188:191], v171 offset:51200
	ds_read_b128 v[192:195], v171 offset:52224
	ds_read_b128 v[196:199], v171 offset:53248
	ds_read_b128 v[200:203], v171 offset:54272
	ds_read_b128 v[204:207], v171 offset:55296
	ds_read_b128 v[208:211], v171 offset:56320
	global_load_lds_dwordx4 v[212:213], off
	s_add_i32 m0, s26, 0x2000
	s_add_u32 s24, s24, 0x20080
	v_lshl_add_u64 v[212:213], v[214:215], 0, s[0:1]
	s_addc_u32 s25, s25, 0
	s_add_i32 s26, s38, s97
	global_load_lds_dwordx4 v[212:213], off
	v_lshl_add_u64 v[212:213], s[24:25], 0, v[148:149]
	s_mov_b32 m0, s26
	s_nop 0
	global_load_lds_dwordx4 v[212:213], off
	v_lshl_add_u64 v[212:213], s[24:25], 0, v[144:145]
	s_add_i32 m0, s26, 0x2000
	s_nop 0
	global_load_lds_dwordx4 v[212:213], off
	v_lshl_add_u64 v[212:213], v[216:217], 0, s[0:1]
	s_mov_b32 m0, s28
	s_nop 0
	global_load_lds_dwordx4 v[212:213], off
	v_lshl_add_u64 v[212:213], v[218:219], 0, s[0:1]
	s_mov_b32 m0, s29
	s_nop 0
	global_load_lds_dwordx4 v[212:213], off
	s_waitcnt vmcnt(8)
	s_waitcnt lgkmcnt(0)
	s_setprio 1
	s_barrier
	v_mfma_f32_16x16x32_bf16 v[48:51], v[128:131], v[180:183], v[48:51]
	v_mfma_f32_16x16x32_bf16 v[52:55], v[136:139], v[180:183], v[52:55]
	v_mfma_f32_16x16x32_bf16 v[32:35], v[128:131], v[188:191], v[32:35]
	v_mfma_f32_16x16x32_bf16 v[36:39], v[136:139], v[188:191], v[36:39]
	v_mfma_f32_16x16x32_bf16 v[16:19], v[128:131], v[196:199], v[16:19]
	v_mfma_f32_16x16x32_bf16 v[20:23], v[136:139], v[196:199], v[20:23]
	v_mfma_f32_16x16x32_bf16 v[0:3], v[128:131], v[204:207], v[0:3]
	v_mfma_f32_16x16x32_bf16 v[4:7], v[136:139], v[204:207], v[4:7]
	v_mfma_f32_16x16x32_bf16 v[48:51], v[132:135], v[184:187], v[48:51]
	v_mfma_f32_16x16x32_bf16 v[52:55], v[140:143], v[184:187], v[52:55]
	v_mfma_f32_16x16x32_bf16 v[32:35], v[132:135], v[192:195], v[32:35]
	v_mfma_f32_16x16x32_bf16 v[36:39], v[140:143], v[192:195], v[36:39]
	v_mfma_f32_16x16x32_bf16 v[16:19], v[132:135], v[200:203], v[16:19]
	v_mfma_f32_16x16x32_bf16 v[20:23], v[140:143], v[200:203], v[20:23]
	v_mfma_f32_16x16x32_bf16 v[0:3], v[132:135], v[208:211], v[0:3]
	v_mfma_f32_16x16x32_bf16 v[4:7], v[140:143], v[208:211], v[4:7]
	v_mfma_f32_16x16x32_bf16 v[56:59], v[158:161], v[180:183], v[56:59]
	v_mfma_f32_16x16x32_bf16 v[60:63], v[172:175], v[180:183], v[60:63]
	v_mfma_f32_16x16x32_bf16 v[40:43], v[158:161], v[188:191], v[40:43]
	v_mfma_f32_16x16x32_bf16 v[44:47], v[172:175], v[188:191], v[44:47]
	v_mfma_f32_16x16x32_bf16 v[24:27], v[158:161], v[196:199], v[24:27]
	v_mfma_f32_16x16x32_bf16 v[28:31], v[172:175], v[196:199], v[28:31]
	v_mfma_f32_16x16x32_bf16 v[8:11], v[158:161], v[204:207], v[8:11]
	v_mfma_f32_16x16x32_bf16 v[12:15], v[172:175], v[204:207], v[12:15]
	v_mfma_f32_16x16x32_bf16 v[56:59], v[162:165], v[184:187], v[56:59]
	v_mfma_f32_16x16x32_bf16 v[60:63], v[176:179], v[184:187], v[60:63]
	v_mfma_f32_16x16x32_bf16 v[40:43], v[162:165], v[192:195], v[40:43]
	v_mfma_f32_16x16x32_bf16 v[44:47], v[176:179], v[192:195], v[44:47]
	v_mfma_f32_16x16x32_bf16 v[24:27], v[162:165], v[200:203], v[24:27]
	v_mfma_f32_16x16x32_bf16 v[28:31], v[176:179], v[200:203], v[28:31]
	v_mfma_f32_16x16x32_bf16 v[8:11], v[162:165], v[208:211], v[8:11]
	v_mfma_f32_16x16x32_bf16 v[12:15], v[176:179], v[208:211], v[12:15]
	s_barrier
	s_setprio 0
	s_add_i32 s36, s36, 2
	s_add_u32 s34, s34, 0x100
	s_addc_u32 s35, s35, 0
	s_add_u32 s22, s22, 0x100
	s_addc_u32 s23, s23, 0
	s_cmp_gt_u32 s36, 5
	s_cbranch_scc0 .LBB0_1693
	v_readlane_b32 s22, v254, 27
	v_readlane_b32 s23, v254, 28
	s_and_b64 vcc, exec, s[22:23]
	s_cbranch_vccz .LBB0_1696
	s_barrier

.LBB0_2020:
	ds_read_b128 v[128:131], v244
	ds_read_b128 v[132:135], v244 offset:1024
	ds_read_b128 v[136:139], v244 offset:2048
	ds_read_b128 v[140:143], v244 offset:3072
	ds_read_b128 v[144:147], v245
	ds_read_b128 v[148:151], v245 offset:1024
	ds_read_b128 v[152:155], v245 offset:2048
	ds_read_b128 v[156:159], v245 offset:3072
	s_add_i32 s71, s46, 2
	s_add_u32 s47, s44, 0xfff00080
	s_addc_u32 s48, s45, -1
	s_cmp_eq_u32 s68, s46
	s_cselect_b32 s46, s43, s69
	s_cselect_b32 s49, s5, s48
	s_cselect_b32 s48, s23, s47
	s_cselect_b32 s47, s21, s70
	v_lshl_add_u64 v[192:193], s[44:45], 0, v[218:219]
	s_add_i32 m0, s94, 0xc000
	ds_read_b128 v[160:163], v246
	ds_read_b128 v[164:167], v246 offset:1024
	ds_read_b128 v[168:171], v246 offset:2048
	ds_read_b128 v[172:175], v246 offset:3072
	ds_read_b128 v[176:179], v246 offset:4096
	ds_read_b128 v[180:183], v246 offset:5120
	ds_read_b128 v[184:187], v246 offset:6144
	ds_read_b128 v[188:191], v246 offset:7168
	global_load_lds_dwordx4 v[192:193], off
	v_lshl_add_u64 v[192:193], s[44:45], 0, v[220:221]
	s_add_i32 m0, s94, 0xe000
	s_nop 0
	global_load_lds_dwordx4 v[192:193], off
	s_waitcnt vmcnt(8)
	s_waitcnt lgkmcnt(0)
	s_setprio 1
	s_barrier
	v_mfma_f32_16x16x32_bf16 v[112:115], v[128:131], v[160:163], v[112:115]
	v_mfma_f32_16x16x32_bf16 v[116:119], v[136:139], v[160:163], v[116:119]
	v_mfma_f32_16x16x32_bf16 v[100:103], v[128:131], v[168:171], v[100:103]
	v_mfma_f32_16x16x32_bf16 v[96:99], v[136:139], v[168:171], v[96:99]
	v_mfma_f32_16x16x32_bf16 v[84:87], v[128:131], v[176:179], v[84:87]
	v_mfma_f32_16x16x32_bf16 v[80:83], v[136:139], v[176:179], v[80:83]
	v_mfma_f32_16x16x32_bf16 v[52:55], v[128:131], v[184:187], v[52:55]
	v_mfma_f32_16x16x32_bf16 v[48:51], v[136:139], v[184:187], v[48:51]
	v_mfma_f32_16x16x32_bf16 v[112:115], v[132:135], v[164:167], v[112:115]
	v_mfma_f32_16x16x32_bf16 v[116:119], v[140:143], v[164:167], v[116:119]
	v_mfma_f32_16x16x32_bf16 v[100:103], v[132:135], v[172:175], v[100:103]
	v_mfma_f32_16x16x32_bf16 v[96:99], v[140:143], v[172:175], v[96:99]
	v_mfma_f32_16x16x32_bf16 v[84:87], v[132:135], v[180:183], v[84:87]
	v_mfma_f32_16x16x32_bf16 v[80:83], v[140:143], v[180:183], v[80:83]
	v_mfma_f32_16x16x32_bf16 v[52:55], v[132:135], v[188:191], v[52:55]
	v_mfma_f32_16x16x32_bf16 v[48:51], v[140:143], v[188:191], v[48:51]
	v_mfma_f32_16x16x32_bf16 v[124:127], v[144:147], v[160:163], v[124:127]
	v_mfma_f32_16x16x32_bf16 v[120:123], v[152:155], v[160:163], v[120:123]
	v_mfma_f32_16x16x32_bf16 v[108:111], v[144:147], v[168:171], v[108:111]
	v_mfma_f32_16x16x32_bf16 v[104:107], v[152:155], v[168:171], v[104:107]
	v_mfma_f32_16x16x32_bf16 v[92:95], v[144:147], v[176:179], v[92:95]
	v_mfma_f32_16x16x32_bf16 v[88:91], v[152:155], v[176:179], v[88:91]
	v_mfma_f32_16x16x32_bf16 v[68:71], v[144:147], v[184:187], v[68:71]
	v_mfma_f32_16x16x32_bf16 v[64:67], v[152:155], v[184:187], v[64:67]
	v_mfma_f32_16x16x32_bf16 v[124:127], v[148:151], v[164:167], v[124:127]
	v_mfma_f32_16x16x32_bf16 v[120:123], v[156:159], v[164:167], v[120:123]
	v_mfma_f32_16x16x32_bf16 v[108:111], v[148:151], v[172:175], v[108:111]
	v_mfma_f32_16x16x32_bf16 v[104:107], v[156:159], v[172:175], v[104:107]
	v_mfma_f32_16x16x32_bf16 v[92:95], v[148:151], v[180:183], v[92:95]
	v_mfma_f32_16x16x32_bf16 v[88:91], v[156:159], v[180:183], v[88:91]
	v_mfma_f32_16x16x32_bf16 v[68:71], v[148:151], v[188:191], v[68:71]
	v_mfma_f32_16x16x32_bf16 v[64:67], v[156:159], v[188:191], v[64:67]
	s_barrier
	s_setprio 0
	s_add_i32 s76, s60, s97
	v_lshl_add_u64 v[192:193], s[46:47], 0, v[210:211]
	s_mov_b32 m0, s76
	ds_read_b128 v[160:163], v246 offset:16384
	ds_read_b128 v[164:167], v246 offset:17408
	ds_read_b128 v[168:171], v246 offset:18432
	ds_read_b128 v[172:175], v246 offset:19456
	ds_read_b128 v[176:179], v246 offset:20480
	ds_read_b128 v[180:183], v246 offset:21504
	ds_read_b128 v[184:187], v246 offset:22528
	ds_read_b128 v[188:191], v246 offset:23552
	global_load_lds_dwordx4 v[192:193], off
	s_add_i32 m0, s76, 0x2000
	s_add_u32 s76, s46, 0x100000
	v_lshl_add_u64 v[194:195], s[46:47], 0, v[214:215]
	s_addc_u32 s77, s47, 0
	s_add_i32 s78, s61, s97
	global_load_lds_dwordx4 v[194:195], off
	v_lshl_add_u64 v[196:197], s[76:77], 0, v[210:211]
	s_mov_b32 m0, s78
	v_lshl_add_u64 v[198:199], s[48:49], 0, v[212:213]
	global_load_lds_dwordx4 v[196:197], off
	v_lshl_add_u64 v[196:197], s[76:77], 0, v[214:215]
	s_add_i32 m0, s78, 0x2000
	s_nop 0
	global_load_lds_dwordx4 v[196:197], off
	v_lshl_add_u64 v[196:197], s[48:49], 0, v[208:209]
	s_mov_b32 m0, s94
	s_nop 0
	global_load_lds_dwordx4 v[196:197], off
	s_mov_b32 m0, s2
	s_nop 0
	global_load_lds_dwordx4 v[198:199], off
	s_waitcnt vmcnt(8)
	s_waitcnt lgkmcnt(0)
	s_setprio 1
	s_barrier
	v_mfma_f32_16x16x32_bf16 v[60:63], v[128:131], v[160:163], v[60:63]
	v_mfma_f32_16x16x32_bf16 v[56:59], v[136:139], v[160:163], v[56:59]
	v_mfma_f32_16x16x32_bf16 v[36:39], v[128:131], v[168:171], v[36:39]
	v_mfma_f32_16x16x32_bf16 v[32:35], v[136:139], v[168:171], v[32:35]
	v_mfma_f32_16x16x32_bf16 v[20:23], v[128:131], v[176:179], v[20:23]
	v_mfma_f32_16x16x32_bf16 v[16:19], v[136:139], v[176:179], v[16:19]
	v_mfma_f32_16x16x32_bf16 v[4:7], v[128:131], v[184:187], v[4:7]
	v_mfma_f32_16x16x32_bf16 v[0:3], v[136:139], v[184:187], v[0:3]
	v_mfma_f32_16x16x32_bf16 v[60:63], v[132:135], v[164:167], v[60:63]
	v_mfma_f32_16x16x32_bf16 v[56:59], v[140:143], v[164:167], v[56:59]
	v_mfma_f32_16x16x32_bf16 v[36:39], v[132:135], v[172:175], v[36:39]
	v_mfma_f32_16x16x32_bf16 v[32:35], v[140:143], v[172:175], v[32:35]
	v_mfma_f32_16x16x32_bf16 v[20:23], v[132:135], v[180:183], v[20:23]
	v_mfma_f32_16x16x32_bf16 v[16:19], v[140:143], v[180:183], v[16:19]
	v_mfma_f32_16x16x32_bf16 v[4:7], v[132:135], v[188:191], v[4:7]
	v_mfma_f32_16x16x32_bf16 v[0:3], v[140:143], v[188:191], v[0:3]
	v_mfma_f32_16x16x32_bf16 v[76:79], v[144:147], v[160:163], v[76:79]
	v_mfma_f32_16x16x32_bf16 v[72:75], v[152:155], v[160:163], v[72:75]
	v_mfma_f32_16x16x32_bf16 v[44:47], v[144:147], v[168:171], v[44:47]
	v_mfma_f32_16x16x32_bf16 v[40:43], v[152:155], v[168:171], v[40:43]
	v_mfma_f32_16x16x32_bf16 v[28:31], v[144:147], v[176:179], v[28:31]
	v_mfma_f32_16x16x32_bf16 v[24:27], v[152:155], v[176:179], v[24:27]
	v_mfma_f32_16x16x32_bf16 v[12:15], v[144:147], v[184:187], v[12:15]
	v_mfma_f32_16x16x32_bf16 v[8:11], v[152:155], v[184:187], v[8:11]
	v_mfma_f32_16x16x32_bf16 v[76:79], v[148:151], v[164:167], v[76:79]
	v_mfma_f32_16x16x32_bf16 v[72:75], v[156:159], v[164:167], v[72:75]
	v_mfma_f32_16x16x32_bf16 v[44:47], v[148:151], v[172:175], v[44:47]
	v_mfma_f32_16x16x32_bf16 v[40:43], v[156:159], v[172:175], v[40:43]
	v_mfma_f32_16x16x32_bf16 v[28:31], v[148:151], v[180:183], v[28:31]
	v_mfma_f32_16x16x32_bf16 v[24:27], v[156:159], v[180:183], v[24:27]
	v_mfma_f32_16x16x32_bf16 v[12:15], v[148:151], v[188:191], v[12:15]
	v_mfma_f32_16x16x32_bf16 v[8:11], v[156:159], v[188:191], v[8:11]
	s_barrier
	s_setprio 0
	s_add_i32 s76, 0, 0x18000
	s_add_i32 s77, 0, 0x1c000
	v_add_u32_e32 v140, s76, v243
	v_add_u32_e32 v156, s77, v243
	ds_read_b128 v[128:131], v140
	ds_read_b128 v[132:135], v140 offset:1024
	ds_read_b128 v[136:139], v140 offset:2048
	ds_read_b128 v[140:143], v140 offset:3072
	ds_read_b128 v[144:147], v156
	ds_read_b128 v[148:151], v156 offset:1024
	ds_read_b128 v[152:155], v156 offset:2048
	ds_read_b128 v[156:159], v156 offset:3072
	s_add_u32 s48, s48, 0x100000
	s_addc_u32 s49, s49, 0
	s_mov_b32 m0, s3
	v_lshl_add_u64 v[200:201], s[48:49], 0, v[208:209]
	ds_read_b128 v[160:163], v246 offset:32768
	ds_read_b128 v[164:167], v246 offset:33792
	ds_read_b128 v[168:171], v246 offset:34816
	ds_read_b128 v[172:175], v246 offset:35840
	ds_read_b128 v[176:179], v246 offset:36864
	ds_read_b128 v[180:183], v246 offset:37888
	ds_read_b128 v[184:187], v246 offset:38912
	ds_read_b128 v[188:191], v246 offset:39936
	global_load_lds_dwordx4 v[200:201], off
	v_lshl_add_u64 v[200:201], s[48:49], 0, v[212:213]
	s_mov_b32 m0, s33
	s_nop 0
	global_load_lds_dwordx4 v[200:201], off
	s_waitcnt vmcnt(8)
	s_waitcnt lgkmcnt(0)
	s_setprio 1
	s_barrier
	v_mfma_f32_16x16x32_bf16 v[112:115], v[128:131], v[160:163], v[112:115]
	v_mfma_f32_16x16x32_bf16 v[116:119], v[136:139], v[160:163], v[116:119]
	v_mfma_f32_16x16x32_bf16 v[100:103], v[128:131], v[168:171], v[100:103]
	v_mfma_f32_16x16x32_bf16 v[96:99], v[136:139], v[168:171], v[96:99]
	v_mfma_f32_16x16x32_bf16 v[84:87], v[128:131], v[176:179], v[84:87]
	v_mfma_f32_16x16x32_bf16 v[80:83], v[136:139], v[176:179], v[80:83]
	v_mfma_f32_16x16x32_bf16 v[52:55], v[128:131], v[184:187], v[52:55]
	v_mfma_f32_16x16x32_bf16 v[48:51], v[136:139], v[184:187], v[48:51]
	v_mfma_f32_16x16x32_bf16 v[112:115], v[132:135], v[164:167], v[112:115]
	v_mfma_f32_16x16x32_bf16 v[116:119], v[140:143], v[164:167], v[116:119]
	v_mfma_f32_16x16x32_bf16 v[100:103], v[132:135], v[172:175], v[100:103]
	v_mfma_f32_16x16x32_bf16 v[96:99], v[140:143], v[172:175], v[96:99]
	v_mfma_f32_16x16x32_bf16 v[84:87], v[132:135], v[180:183], v[84:87]
	v_mfma_f32_16x16x32_bf16 v[80:83], v[140:143], v[180:183], v[80:83]
	v_mfma_f32_16x16x32_bf16 v[52:55], v[132:135], v[188:191], v[52:55]
	v_mfma_f32_16x16x32_bf16 v[48:51], v[140:143], v[188:191], v[48:51]
	v_mfma_f32_16x16x32_bf16 v[124:127], v[144:147], v[160:163], v[124:127]
	v_mfma_f32_16x16x32_bf16 v[120:123], v[152:155], v[160:163], v[120:123]
	v_mfma_f32_16x16x32_bf16 v[108:111], v[144:147], v[168:171], v[108:111]
	v_mfma_f32_16x16x32_bf16 v[104:107], v[152:155], v[168:171], v[104:107]
	v_mfma_f32_16x16x32_bf16 v[92:95], v[144:147], v[176:179], v[92:95]
	v_mfma_f32_16x16x32_bf16 v[88:91], v[152:155], v[176:179], v[88:91]
	v_mfma_f32_16x16x32_bf16 v[68:71], v[144:147], v[184:187], v[68:71]
	v_mfma_f32_16x16x32_bf16 v[64:67], v[152:155], v[184:187], v[64:67]
	v_mfma_f32_16x16x32_bf16 v[124:127], v[148:151], v[164:167], v[124:127]
	v_mfma_f32_16x16x32_bf16 v[120:123], v[156:159], v[164:167], v[120:123]
	v_mfma_f32_16x16x32_bf16 v[108:111], v[148:151], v[172:175], v[108:111]
	v_mfma_f32_16x16x32_bf16 v[104:107], v[156:159], v[172:175], v[104:107]
	v_mfma_f32_16x16x32_bf16 v[92:95], v[148:151], v[180:183], v[92:95]
	v_mfma_f32_16x16x32_bf16 v[88:91], v[156:159], v[180:183], v[88:91]
	v_mfma_f32_16x16x32_bf16 v[68:71], v[148:151], v[188:191], v[68:71]
	v_mfma_f32_16x16x32_bf16 v[64:67], v[156:159], v[188:191], v[64:67]
	s_barrier
	s_setprio 0
	s_add_i32 s48, s76, s97
	v_lshl_add_u64 v[192:193], v[192:193], 0, s[16:17]
	s_mov_b32 m0, s48
	ds_read_b128 v[160:163], v246 offset:49152
	ds_read_b128 v[164:167], v246 offset:50176
	ds_read_b128 v[168:171], v246 offset:51200
	ds_read_b128 v[172:175], v246 offset:52224
	ds_read_b128 v[176:179], v246 offset:53248
	ds_read_b128 v[180:183], v246 offset:54272
	ds_read_b128 v[184:187], v246 offset:55296
	ds_read_b128 v[188:191], v246 offset:56320
	global_load_lds_dwordx4 v[192:193], off
	s_add_i32 m0, s48, 0x2000
	s_add_u32 s46, s46, 0x100080
	v_lshl_add_u64 v[192:193], v[194:195], 0, s[16:17]
	s_addc_u32 s47, s47, 0
	s_add_i32 s48, s77, s97
	global_load_lds_dwordx4 v[192:193], off
	v_lshl_add_u64 v[192:193], s[46:47], 0, v[210:211]
	s_mov_b32 m0, s48
	s_nop 0
	global_load_lds_dwordx4 v[192:193], off
	v_lshl_add_u64 v[192:193], s[46:47], 0, v[214:215]
	s_add_i32 m0, s48, 0x2000
	s_nop 0
	global_load_lds_dwordx4 v[192:193], off
	v_lshl_add_u64 v[192:193], v[196:197], 0, s[16:17]
	s_mov_b32 m0, s54
	s_nop 0
	global_load_lds_dwordx4 v[192:193], off
	v_lshl_add_u64 v[192:193], v[198:199], 0, s[16:17]
	s_mov_b32 m0, s55
	s_nop 0
	global_load_lds_dwordx4 v[192:193], off
	s_waitcnt vmcnt(8)
	s_waitcnt lgkmcnt(0)
	s_setprio 1
	s_barrier
	v_mfma_f32_16x16x32_bf16 v[60:63], v[128:131], v[160:163], v[60:63]
	v_mfma_f32_16x16x32_bf16 v[56:59], v[136:139], v[160:163], v[56:59]
	v_mfma_f32_16x16x32_bf16 v[36:39], v[128:131], v[168:171], v[36:39]
	v_mfma_f32_16x16x32_bf16 v[32:35], v[136:139], v[168:171], v[32:35]
	v_mfma_f32_16x16x32_bf16 v[20:23], v[128:131], v[176:179], v[20:23]
	v_mfma_f32_16x16x32_bf16 v[16:19], v[136:139], v[176:179], v[16:19]
	v_mfma_f32_16x16x32_bf16 v[4:7], v[128:131], v[184:187], v[4:7]
	v_mfma_f32_16x16x32_bf16 v[0:3], v[136:139], v[184:187], v[0:3]
	v_mfma_f32_16x16x32_bf16 v[60:63], v[132:135], v[164:167], v[60:63]
	v_mfma_f32_16x16x32_bf16 v[56:59], v[140:143], v[164:167], v[56:59]
	v_mfma_f32_16x16x32_bf16 v[36:39], v[132:135], v[172:175], v[36:39]
	v_mfma_f32_16x16x32_bf16 v[32:35], v[140:143], v[172:175], v[32:35]
	v_mfma_f32_16x16x32_bf16 v[20:23], v[132:135], v[180:183], v[20:23]
	v_mfma_f32_16x16x32_bf16 v[16:19], v[140:143], v[180:183], v[16:19]
	v_mfma_f32_16x16x32_bf16 v[4:7], v[132:135], v[188:191], v[4:7]
	v_mfma_f32_16x16x32_bf16 v[0:3], v[140:143], v[188:191], v[0:3]
	v_mfma_f32_16x16x32_bf16 v[76:79], v[144:147], v[160:163], v[76:79]
	v_mfma_f32_16x16x32_bf16 v[72:75], v[152:155], v[160:163], v[72:75]
	v_mfma_f32_16x16x32_bf16 v[44:47], v[144:147], v[168:171], v[44:47]
	v_mfma_f32_16x16x32_bf16 v[40:43], v[152:155], v[168:171], v[40:43]
	v_mfma_f32_16x16x32_bf16 v[28:31], v[144:147], v[176:179], v[28:31]
	v_mfma_f32_16x16x32_bf16 v[24:27], v[152:155], v[176:179], v[24:27]
	v_mfma_f32_16x16x32_bf16 v[12:15], v[144:147], v[184:187], v[12:15]
	v_mfma_f32_16x16x32_bf16 v[8:11], v[152:155], v[184:187], v[8:11]
	v_mfma_f32_16x16x32_bf16 v[76:79], v[148:151], v[164:167], v[76:79]
	v_mfma_f32_16x16x32_bf16 v[72:75], v[156:159], v[164:167], v[72:75]
	v_mfma_f32_16x16x32_bf16 v[44:47], v[148:151], v[172:175], v[44:47]
	v_mfma_f32_16x16x32_bf16 v[40:43], v[156:159], v[172:175], v[40:43]
	v_mfma_f32_16x16x32_bf16 v[28:31], v[148:151], v[180:183], v[28:31]
	v_mfma_f32_16x16x32_bf16 v[24:27], v[156:159], v[180:183], v[24:27]
	v_mfma_f32_16x16x32_bf16 v[12:15], v[148:151], v[188:191], v[12:15]
	v_mfma_f32_16x16x32_bf16 v[8:11], v[156:159], v[188:191], v[8:11]
	s_barrier
	s_setprio 0
	s_add_u32 s69, s69, 0x100
	s_addc_u32 s70, s70, 0
	s_add_u32 s44, s44, 0x100
	s_addc_u32 s45, s45, 0
	s_cmp_ge_u32 s71, s67
	s_mov_b32 s46, s71
	s_cbranch_scc0 .LBB0_2020
	v_readlane_b32 s44, v254, 27
	v_readlane_b32 s45, v254, 28
	s_and_b64 vcc, exec, s[44:45]
	s_cbranch_vccz .LBB0_2028
	s_barrier
	s_cmp_lt_i32 s14, 0
	s_mov_b64 s[44:45], -1
	s_cbranch_scc1 .LBB0_2029

.LBB0_2289:
	ds_read_b128 v[148:151], v159
	ds_read_b128 v[164:167], v159 offset:1024
	ds_read_b128 v[168:171], v159 offset:2048
	ds_read_b128 v[172:175], v159 offset:3072
	ds_read_b128 v[176:179], v160
	ds_read_b128 v[180:183], v160 offset:1024
	ds_read_b128 v[184:187], v160 offset:2048
	ds_read_b128 v[188:191], v160 offset:3072
	s_add_i32 s87, s46, 2
	s_add_u32 s47, s44, 0xfff00080
	s_addc_u32 s48, s45, -1
	s_cmp_eq_u32 s43, s46
	s_cselect_b32 s46, s25, s85
	s_cselect_b32 s49, s37, s48
	s_cselect_b32 s48, s36, s47
	s_cselect_b32 s47, s5, s86
	v_lshl_add_u64 v[152:153], s[44:45], 0, v[142:143]
	s_add_i32 m0, s94, 0xc000
	ds_read_b128 v[192:195], v161
	ds_read_b128 v[196:199], v161 offset:1024
	ds_read_b128 v[200:203], v161 offset:2048
	ds_read_b128 v[204:207], v161 offset:3072
	ds_read_b128 v[208:211], v161 offset:4096
	ds_read_b128 v[212:215], v161 offset:5120
	ds_read_b128 v[216:219], v161 offset:6144
	ds_read_b128 v[220:223], v161 offset:7168
	global_load_lds_dwordx4 v[152:153], off
	v_lshl_add_u64 v[152:153], s[44:45], 0, v[144:145]
	s_add_i32 m0, s94, 0xe000
	s_nop 0
	global_load_lds_dwordx4 v[152:153], off
	s_waitcnt vmcnt(8)
	s_waitcnt lgkmcnt(0)
	s_setprio 1
	s_barrier
	v_mfma_f32_16x16x32_bf16 v[112:115], v[148:151], v[192:195], v[112:115]
	v_mfma_f32_16x16x32_bf16 v[116:119], v[168:171], v[192:195], v[116:119]
	v_mfma_f32_16x16x32_bf16 v[100:103], v[148:151], v[200:203], v[100:103]
	v_mfma_f32_16x16x32_bf16 v[96:99], v[168:171], v[200:203], v[96:99]
	v_mfma_f32_16x16x32_bf16 v[84:87], v[148:151], v[208:211], v[84:87]
	v_mfma_f32_16x16x32_bf16 v[80:83], v[168:171], v[208:211], v[80:83]
	v_mfma_f32_16x16x32_bf16 v[52:55], v[148:151], v[216:219], v[52:55]
	v_mfma_f32_16x16x32_bf16 v[48:51], v[168:171], v[216:219], v[48:51]
	v_mfma_f32_16x16x32_bf16 v[112:115], v[164:167], v[196:199], v[112:115]
	v_mfma_f32_16x16x32_bf16 v[116:119], v[172:175], v[196:199], v[116:119]
	v_mfma_f32_16x16x32_bf16 v[100:103], v[164:167], v[204:207], v[100:103]
	v_mfma_f32_16x16x32_bf16 v[96:99], v[172:175], v[204:207], v[96:99]
	v_mfma_f32_16x16x32_bf16 v[84:87], v[164:167], v[212:215], v[84:87]
	v_mfma_f32_16x16x32_bf16 v[80:83], v[172:175], v[212:215], v[80:83]
	v_mfma_f32_16x16x32_bf16 v[52:55], v[164:167], v[220:223], v[52:55]
	v_mfma_f32_16x16x32_bf16 v[48:51], v[172:175], v[220:223], v[48:51]
	v_mfma_f32_16x16x32_bf16 v[124:127], v[176:179], v[192:195], v[124:127]
	v_mfma_f32_16x16x32_bf16 v[120:123], v[184:187], v[192:195], v[120:123]
	v_mfma_f32_16x16x32_bf16 v[108:111], v[176:179], v[200:203], v[108:111]
	v_mfma_f32_16x16x32_bf16 v[104:107], v[184:187], v[200:203], v[104:107]
	v_mfma_f32_16x16x32_bf16 v[92:95], v[176:179], v[208:211], v[92:95]
	v_mfma_f32_16x16x32_bf16 v[88:91], v[184:187], v[208:211], v[88:91]
	v_mfma_f32_16x16x32_bf16 v[68:71], v[176:179], v[216:219], v[68:71]
	v_mfma_f32_16x16x32_bf16 v[64:67], v[184:187], v[216:219], v[64:67]
	v_mfma_f32_16x16x32_bf16 v[124:127], v[180:183], v[196:199], v[124:127]
	v_mfma_f32_16x16x32_bf16 v[120:123], v[188:191], v[196:199], v[120:123]
	v_mfma_f32_16x16x32_bf16 v[108:111], v[180:183], v[204:207], v[108:111]
	v_mfma_f32_16x16x32_bf16 v[104:107], v[188:191], v[204:207], v[104:107]
	v_mfma_f32_16x16x32_bf16 v[92:95], v[180:183], v[212:215], v[92:95]
	v_mfma_f32_16x16x32_bf16 v[88:91], v[188:191], v[212:215], v[88:91]
	v_mfma_f32_16x16x32_bf16 v[68:71], v[180:183], v[220:223], v[68:71]
	v_mfma_f32_16x16x32_bf16 v[64:67], v[188:191], v[220:223], v[64:67]
	s_barrier
	s_setprio 0
	s_add_i32 s88, s77, s97
	v_lshl_add_u64 v[152:153], s[46:47], 0, v[132:133]
	s_mov_b32 m0, s88
	ds_read_b128 v[192:195], v161 offset:16384
	ds_read_b128 v[196:199], v161 offset:17408
	ds_read_b128 v[200:203], v161 offset:18432
	ds_read_b128 v[204:207], v161 offset:19456
	ds_read_b128 v[208:211], v161 offset:20480
	ds_read_b128 v[212:215], v161 offset:21504
	ds_read_b128 v[216:219], v161 offset:22528
	ds_read_b128 v[220:223], v161 offset:23552
	global_load_lds_dwordx4 v[152:153], off
	s_add_i32 m0, s88, 0x2000
	s_add_u32 s88, s46, 0x100000
	v_lshl_add_u64 v[224:225], s[46:47], 0, v[136:137]
	s_addc_u32 s89, s47, 0
	s_add_i32 s90, s78, s97
	global_load_lds_dwordx4 v[224:225], off
	v_lshl_add_u64 v[226:227], s[88:89], 0, v[132:133]
	s_mov_b32 m0, s90
	v_lshl_add_u64 v[228:229], s[48:49], 0, v[134:135]
	global_load_lds_dwordx4 v[226:227], off
	v_lshl_add_u64 v[226:227], s[88:89], 0, v[136:137]
	s_add_i32 m0, s90, 0x2000
	s_nop 0
	global_load_lds_dwordx4 v[226:227], off
	v_lshl_add_u64 v[226:227], s[48:49], 0, v[130:131]
	s_mov_b32 m0, s94
	s_nop 0
	global_load_lds_dwordx4 v[226:227], off
	s_mov_b32 m0, s52
	s_nop 0
	global_load_lds_dwordx4 v[228:229], off
	s_waitcnt vmcnt(8)
	s_waitcnt lgkmcnt(0)
	s_setprio 1
	s_barrier
	v_mfma_f32_16x16x32_bf16 v[60:63], v[148:151], v[192:195], v[60:63]
	v_mfma_f32_16x16x32_bf16 v[56:59], v[168:171], v[192:195], v[56:59]
	v_mfma_f32_16x16x32_bf16 v[36:39], v[148:151], v[200:203], v[36:39]
	v_mfma_f32_16x16x32_bf16 v[32:35], v[168:171], v[200:203], v[32:35]
	v_mfma_f32_16x16x32_bf16 v[20:23], v[148:151], v[208:211], v[20:23]
	v_mfma_f32_16x16x32_bf16 v[16:19], v[168:171], v[208:211], v[16:19]
	v_mfma_f32_16x16x32_bf16 v[4:7], v[148:151], v[216:219], v[4:7]
	v_mfma_f32_16x16x32_bf16 v[0:3], v[168:171], v[216:219], v[0:3]
	v_mfma_f32_16x16x32_bf16 v[60:63], v[164:167], v[196:199], v[60:63]
	v_mfma_f32_16x16x32_bf16 v[56:59], v[172:175], v[196:199], v[56:59]
	v_mfma_f32_16x16x32_bf16 v[36:39], v[164:167], v[204:207], v[36:39]
	v_mfma_f32_16x16x32_bf16 v[32:35], v[172:175], v[204:207], v[32:35]
	v_mfma_f32_16x16x32_bf16 v[20:23], v[164:167], v[212:215], v[20:23]
	v_mfma_f32_16x16x32_bf16 v[16:19], v[172:175], v[212:215], v[16:19]
	v_mfma_f32_16x16x32_bf16 v[4:7], v[164:167], v[220:223], v[4:7]
	v_mfma_f32_16x16x32_bf16 v[0:3], v[172:175], v[220:223], v[0:3]
	v_mfma_f32_16x16x32_bf16 v[76:79], v[176:179], v[192:195], v[76:79]
	v_mfma_f32_16x16x32_bf16 v[72:75], v[184:187], v[192:195], v[72:75]
	v_mfma_f32_16x16x32_bf16 v[44:47], v[176:179], v[200:203], v[44:47]
	v_mfma_f32_16x16x32_bf16 v[40:43], v[184:187], v[200:203], v[40:43]
	v_mfma_f32_16x16x32_bf16 v[28:31], v[176:179], v[208:211], v[28:31]
	v_mfma_f32_16x16x32_bf16 v[24:27], v[184:187], v[208:211], v[24:27]
	v_mfma_f32_16x16x32_bf16 v[12:15], v[176:179], v[216:219], v[12:15]
	v_mfma_f32_16x16x32_bf16 v[8:11], v[184:187], v[216:219], v[8:11]
	v_mfma_f32_16x16x32_bf16 v[76:79], v[180:183], v[196:199], v[76:79]
	v_mfma_f32_16x16x32_bf16 v[72:75], v[188:191], v[196:199], v[72:75]
	v_mfma_f32_16x16x32_bf16 v[44:47], v[180:183], v[204:207], v[44:47]
	v_mfma_f32_16x16x32_bf16 v[40:43], v[188:191], v[204:207], v[40:43]
	v_mfma_f32_16x16x32_bf16 v[28:31], v[180:183], v[212:215], v[28:31]
	v_mfma_f32_16x16x32_bf16 v[24:27], v[188:191], v[212:215], v[24:27]
	v_mfma_f32_16x16x32_bf16 v[12:15], v[180:183], v[220:223], v[12:15]
	v_mfma_f32_16x16x32_bf16 v[8:11], v[188:191], v[220:223], v[8:11]
	s_barrier
	s_setprio 0
	s_add_i32 s88, 0, 0x18000
	v_add_u32_e32 v163, s88, v157
	s_add_i32 s89, 0, 0x1c000
	ds_read_b128 v[148:151], v163
	ds_read_b128 v[164:167], v163 offset:1024
	ds_read_b128 v[168:171], v163 offset:2048
	ds_read_b128 v[172:175], v163 offset:3072
	v_add_u32_e32 v163, s89, v157
	ds_read_b128 v[176:179], v163
	ds_read_b128 v[180:183], v163 offset:1024
	ds_read_b128 v[184:187], v163 offset:2048
	ds_read_b128 v[188:191], v163 offset:3072
	s_add_u32 s48, s48, 0x100000
	s_addc_u32 s49, s49, 0
	s_mov_b32 m0, s53
	v_lshl_add_u64 v[230:231], s[48:49], 0, v[130:131]
	ds_read_b128 v[192:195], v161 offset:32768
	ds_read_b128 v[196:199], v161 offset:33792
	ds_read_b128 v[200:203], v161 offset:34816
	ds_read_b128 v[204:207], v161 offset:35840
	ds_read_b128 v[208:211], v161 offset:36864
	ds_read_b128 v[212:215], v161 offset:37888
	ds_read_b128 v[216:219], v161 offset:38912
	ds_read_b128 v[220:223], v161 offset:39936
	global_load_lds_dwordx4 v[230:231], off
	v_lshl_add_u64 v[230:231], s[48:49], 0, v[134:135]
	s_mov_b32 m0, s54
	s_nop 0
	global_load_lds_dwordx4 v[230:231], off
	s_waitcnt vmcnt(8)
	s_waitcnt lgkmcnt(0)
	s_setprio 1
	s_barrier
	v_mfma_f32_16x16x32_bf16 v[112:115], v[148:151], v[192:195], v[112:115]
	v_mfma_f32_16x16x32_bf16 v[116:119], v[168:171], v[192:195], v[116:119]
	v_mfma_f32_16x16x32_bf16 v[100:103], v[148:151], v[200:203], v[100:103]
	v_mfma_f32_16x16x32_bf16 v[96:99], v[168:171], v[200:203], v[96:99]
	v_mfma_f32_16x16x32_bf16 v[84:87], v[148:151], v[208:211], v[84:87]
	v_mfma_f32_16x16x32_bf16 v[80:83], v[168:171], v[208:211], v[80:83]
	v_mfma_f32_16x16x32_bf16 v[52:55], v[148:151], v[216:219], v[52:55]
	v_mfma_f32_16x16x32_bf16 v[48:51], v[168:171], v[216:219], v[48:51]
	v_mfma_f32_16x16x32_bf16 v[112:115], v[164:167], v[196:199], v[112:115]
	v_mfma_f32_16x16x32_bf16 v[116:119], v[172:175], v[196:199], v[116:119]
	v_mfma_f32_16x16x32_bf16 v[100:103], v[164:167], v[204:207], v[100:103]
	v_mfma_f32_16x16x32_bf16 v[96:99], v[172:175], v[204:207], v[96:99]
	v_mfma_f32_16x16x32_bf16 v[84:87], v[164:167], v[212:215], v[84:87]
	v_mfma_f32_16x16x32_bf16 v[80:83], v[172:175], v[212:215], v[80:83]
	v_mfma_f32_16x16x32_bf16 v[52:55], v[164:167], v[220:223], v[52:55]
	v_mfma_f32_16x16x32_bf16 v[48:51], v[172:175], v[220:223], v[48:51]
	v_mfma_f32_16x16x32_bf16 v[124:127], v[176:179], v[192:195], v[124:127]
	v_mfma_f32_16x16x32_bf16 v[120:123], v[184:187], v[192:195], v[120:123]
	v_mfma_f32_16x16x32_bf16 v[108:111], v[176:179], v[200:203], v[108:111]
	v_mfma_f32_16x16x32_bf16 v[104:107], v[184:187], v[200:203], v[104:107]
	v_mfma_f32_16x16x32_bf16 v[92:95], v[176:179], v[208:211], v[92:95]
	v_mfma_f32_16x16x32_bf16 v[88:91], v[184:187], v[208:211], v[88:91]
	v_mfma_f32_16x16x32_bf16 v[68:71], v[176:179], v[216:219], v[68:71]
	v_mfma_f32_16x16x32_bf16 v[64:67], v[184:187], v[216:219], v[64:67]
	v_mfma_f32_16x16x32_bf16 v[124:127], v[180:183], v[196:199], v[124:127]
	v_mfma_f32_16x16x32_bf16 v[120:123], v[188:191], v[196:199], v[120:123]
	v_mfma_f32_16x16x32_bf16 v[108:111], v[180:183], v[204:207], v[108:111]
	v_mfma_f32_16x16x32_bf16 v[104:107], v[188:191], v[204:207], v[104:107]
	v_mfma_f32_16x16x32_bf16 v[92:95], v[180:183], v[212:215], v[92:95]
	v_mfma_f32_16x16x32_bf16 v[88:91], v[188:191], v[212:215], v[88:91]
	v_mfma_f32_16x16x32_bf16 v[68:71], v[180:183], v[220:223], v[68:71]
	v_mfma_f32_16x16x32_bf16 v[64:67], v[188:191], v[220:223], v[64:67]
	s_barrier
	s_setprio 0
	s_add_i32 s48, s88, s97
	v_lshl_add_u64 v[152:153], v[152:153], 0, s[18:19]
	s_mov_b32 m0, s48
	ds_read_b128 v[192:195], v161 offset:49152
	ds_read_b128 v[196:199], v161 offset:50176
	ds_read_b128 v[200:203], v161 offset:51200
	ds_read_b128 v[204:207], v161 offset:52224
	ds_read_b128 v[208:211], v161 offset:53248
	ds_read_b128 v[212:215], v161 offset:54272
	ds_read_b128 v[216:219], v161 offset:55296
	ds_read_b128 v[220:223], v161 offset:56320
	global_load_lds_dwordx4 v[152:153], off
	s_add_i32 m0, s48, 0x2000
	s_add_u32 s46, s46, 0x100080
	v_lshl_add_u64 v[152:153], v[224:225], 0, s[18:19]
	s_addc_u32 s47, s47, 0
	s_add_i32 s48, s89, s97
	global_load_lds_dwordx4 v[152:153], off
	v_lshl_add_u64 v[152:153], s[46:47], 0, v[132:133]
	s_mov_b32 m0, s48
	s_nop 0
	global_load_lds_dwordx4 v[152:153], off
	v_lshl_add_u64 v[152:153], s[46:47], 0, v[136:137]
	s_add_i32 m0, s48, 0x2000
	s_nop 0
	global_load_lds_dwordx4 v[152:153], off
	v_lshl_add_u64 v[152:153], v[226:227], 0, s[18:19]
	s_mov_b32 m0, s68
	s_nop 0
	global_load_lds_dwordx4 v[152:153], off
	v_lshl_add_u64 v[152:153], v[228:229], 0, s[18:19]
	s_mov_b32 m0, s69
	s_nop 0
	global_load_lds_dwordx4 v[152:153], off
	s_waitcnt vmcnt(8)
	s_waitcnt lgkmcnt(0)
	s_setprio 1
	s_barrier
	v_mfma_f32_16x16x32_bf16 v[60:63], v[148:151], v[192:195], v[60:63]
	v_mfma_f32_16x16x32_bf16 v[56:59], v[168:171], v[192:195], v[56:59]
	v_mfma_f32_16x16x32_bf16 v[36:39], v[148:151], v[200:203], v[36:39]
	v_mfma_f32_16x16x32_bf16 v[32:35], v[168:171], v[200:203], v[32:35]
	v_mfma_f32_16x16x32_bf16 v[20:23], v[148:151], v[208:211], v[20:23]
	v_mfma_f32_16x16x32_bf16 v[16:19], v[168:171], v[208:211], v[16:19]
	v_mfma_f32_16x16x32_bf16 v[4:7], v[148:151], v[216:219], v[4:7]
	v_mfma_f32_16x16x32_bf16 v[0:3], v[168:171], v[216:219], v[0:3]
	v_mfma_f32_16x16x32_bf16 v[60:63], v[164:167], v[196:199], v[60:63]
	v_mfma_f32_16x16x32_bf16 v[56:59], v[172:175], v[196:199], v[56:59]
	v_mfma_f32_16x16x32_bf16 v[36:39], v[164:167], v[204:207], v[36:39]
	v_mfma_f32_16x16x32_bf16 v[32:35], v[172:175], v[204:207], v[32:35]
	v_mfma_f32_16x16x32_bf16 v[20:23], v[164:167], v[212:215], v[20:23]
	v_mfma_f32_16x16x32_bf16 v[16:19], v[172:175], v[212:215], v[16:19]
	v_mfma_f32_16x16x32_bf16 v[4:7], v[164:167], v[220:223], v[4:7]
	v_mfma_f32_16x16x32_bf16 v[0:3], v[172:175], v[220:223], v[0:3]
	v_mfma_f32_16x16x32_bf16 v[76:79], v[176:179], v[192:195], v[76:79]
	v_mfma_f32_16x16x32_bf16 v[72:75], v[184:187], v[192:195], v[72:75]
	v_mfma_f32_16x16x32_bf16 v[44:47], v[176:179], v[200:203], v[44:47]
	v_mfma_f32_16x16x32_bf16 v[40:43], v[184:187], v[200:203], v[40:43]
	v_mfma_f32_16x16x32_bf16 v[28:31], v[176:179], v[208:211], v[28:31]
	v_mfma_f32_16x16x32_bf16 v[24:27], v[184:187], v[208:211], v[24:27]
	v_mfma_f32_16x16x32_bf16 v[12:15], v[176:179], v[216:219], v[12:15]
	v_mfma_f32_16x16x32_bf16 v[8:11], v[184:187], v[216:219], v[8:11]
	v_mfma_f32_16x16x32_bf16 v[76:79], v[180:183], v[196:199], v[76:79]
	v_mfma_f32_16x16x32_bf16 v[72:75], v[188:191], v[196:199], v[72:75]
	v_mfma_f32_16x16x32_bf16 v[44:47], v[180:183], v[204:207], v[44:47]
	v_mfma_f32_16x16x32_bf16 v[40:43], v[188:191], v[204:207], v[40:43]
	v_mfma_f32_16x16x32_bf16 v[28:31], v[180:183], v[212:215], v[28:31]
	v_mfma_f32_16x16x32_bf16 v[24:27], v[188:191], v[212:215], v[24:27]
	v_mfma_f32_16x16x32_bf16 v[12:15], v[180:183], v[220:223], v[12:15]
	v_mfma_f32_16x16x32_bf16 v[8:11], v[188:191], v[220:223], v[8:11]
	s_barrier
	s_setprio 0
	s_add_u32 s85, s85, 0x100
	s_addc_u32 s86, s86, 0
	s_add_u32 s44, s44, 0x100
	s_addc_u32 s45, s45, 0
	s_cmp_ge_u32 s87, s84
	s_mov_b32 s46, s87
	s_cbranch_scc0 .LBB0_2289
	v_readlane_b32 s44, v254, 27
	v_readlane_b32 s45, v254, 28
	s_and_b64 vcc, exec, s[44:45]
	s_cbranch_vccz .LBB0_2297
	s_barrier
	s_cmp_lt_i32 s16, 0
	s_mov_b64 s[44:45], -1
	s_cbranch_scc1 .LBB0_2298

.LBB0_2453:
	ds_read_b128 v[128:131], v228
	ds_read_b128 v[132:135], v228 offset:1024
	ds_read_b128 v[136:139], v228 offset:2048
	ds_read_b128 v[140:143], v228 offset:3072
	ds_read_b128 v[144:147], v229
	ds_read_b128 v[148:151], v229 offset:1024
	ds_read_b128 v[152:155], v229 offset:2048
	ds_read_b128 v[156:159], v229 offset:3072
	s_add_i32 s79, s46, 2
	s_add_u32 s47, s44, 0xffc00080
	s_addc_u32 s48, s45, -1
	s_cmp_eq_u32 s75, s46
	s_cselect_b32 s46, s43, s77
	s_cselect_b32 s49, s35, s48
	s_cselect_b32 s48, s41, s47
	s_cselect_b32 s47, s31, s78
	v_lshl_add_u64 v[208:209], s[44:45], 0, v[202:203]
	s_add_i32 m0, s94, 0xc000
	ds_read_b128 v[160:163], v230
	ds_read_b128 v[164:167], v230 offset:1024
	ds_read_b128 v[168:171], v230 offset:2048
	ds_read_b128 v[172:175], v230 offset:3072
	ds_read_b128 v[176:179], v230 offset:4096
	ds_read_b128 v[180:183], v230 offset:5120
	ds_read_b128 v[184:187], v230 offset:6144
	ds_read_b128 v[188:191], v230 offset:7168
	global_load_lds_dwordx4 v[208:209], off
	v_lshl_add_u64 v[208:209], s[44:45], 0, v[204:205]
	s_add_i32 m0, s94, 0xe000
	s_nop 0
	global_load_lds_dwordx4 v[208:209], off
	s_waitcnt vmcnt(8)
	s_waitcnt lgkmcnt(0)
	s_setprio 1
	s_barrier
	v_mfma_f32_16x16x32_bf16 v[112:115], v[128:131], v[160:163], v[112:115]
	v_mfma_f32_16x16x32_bf16 v[116:119], v[136:139], v[160:163], v[116:119]
	v_mfma_f32_16x16x32_bf16 v[100:103], v[128:131], v[168:171], v[100:103]
	v_mfma_f32_16x16x32_bf16 v[96:99], v[136:139], v[168:171], v[96:99]
	v_mfma_f32_16x16x32_bf16 v[84:87], v[128:131], v[176:179], v[84:87]
	v_mfma_f32_16x16x32_bf16 v[80:83], v[136:139], v[176:179], v[80:83]
	v_mfma_f32_16x16x32_bf16 v[52:55], v[128:131], v[184:187], v[52:55]
	v_mfma_f32_16x16x32_bf16 v[48:51], v[136:139], v[184:187], v[48:51]
	v_mfma_f32_16x16x32_bf16 v[112:115], v[132:135], v[164:167], v[112:115]
	v_mfma_f32_16x16x32_bf16 v[116:119], v[140:143], v[164:167], v[116:119]
	v_mfma_f32_16x16x32_bf16 v[100:103], v[132:135], v[172:175], v[100:103]
	v_mfma_f32_16x16x32_bf16 v[96:99], v[140:143], v[172:175], v[96:99]
	v_mfma_f32_16x16x32_bf16 v[84:87], v[132:135], v[180:183], v[84:87]
	v_mfma_f32_16x16x32_bf16 v[80:83], v[140:143], v[180:183], v[80:83]
	v_mfma_f32_16x16x32_bf16 v[52:55], v[132:135], v[188:191], v[52:55]
	v_mfma_f32_16x16x32_bf16 v[48:51], v[140:143], v[188:191], v[48:51]
	v_mfma_f32_16x16x32_bf16 v[124:127], v[144:147], v[160:163], v[124:127]
	v_mfma_f32_16x16x32_bf16 v[120:123], v[152:155], v[160:163], v[120:123]
	v_mfma_f32_16x16x32_bf16 v[108:111], v[144:147], v[168:171], v[108:111]
	v_mfma_f32_16x16x32_bf16 v[104:107], v[152:155], v[168:171], v[104:107]
	v_mfma_f32_16x16x32_bf16 v[92:95], v[144:147], v[176:179], v[92:95]
	v_mfma_f32_16x16x32_bf16 v[88:91], v[152:155], v[176:179], v[88:91]
	v_mfma_f32_16x16x32_bf16 v[68:71], v[144:147], v[184:187], v[68:71]
	v_mfma_f32_16x16x32_bf16 v[64:67], v[152:155], v[184:187], v[64:67]
	v_mfma_f32_16x16x32_bf16 v[124:127], v[148:151], v[164:167], v[124:127]
	v_mfma_f32_16x16x32_bf16 v[120:123], v[156:159], v[164:167], v[120:123]
	v_mfma_f32_16x16x32_bf16 v[108:111], v[148:151], v[172:175], v[108:111]
	v_mfma_f32_16x16x32_bf16 v[104:107], v[156:159], v[172:175], v[104:107]
	v_mfma_f32_16x16x32_bf16 v[92:95], v[148:151], v[180:183], v[92:95]
	v_mfma_f32_16x16x32_bf16 v[88:91], v[156:159], v[180:183], v[88:91]
	v_mfma_f32_16x16x32_bf16 v[68:71], v[148:151], v[188:191], v[68:71]
	v_mfma_f32_16x16x32_bf16 v[64:67], v[156:159], v[188:191], v[64:67]
	s_barrier
	s_setprio 0
	s_add_i32 s80, s68, s97
	v_lshl_add_u64 v[208:209], s[46:47], 0, v[194:195]
	s_mov_b32 m0, s80
	ds_read_b128 v[160:163], v230 offset:16384
	ds_read_b128 v[164:167], v230 offset:17408
	ds_read_b128 v[168:171], v230 offset:18432
	ds_read_b128 v[172:175], v230 offset:19456
	ds_read_b128 v[176:179], v230 offset:20480
	ds_read_b128 v[180:183], v230 offset:21504
	ds_read_b128 v[184:187], v230 offset:22528
	ds_read_b128 v[188:191], v230 offset:23552
	global_load_lds_dwordx4 v[208:209], off
	s_add_i32 m0, s80, 0x2000
	s_add_u32 s80, s46, 0x400000
	v_lshl_add_u64 v[210:211], s[46:47], 0, v[198:199]
	s_addc_u32 s81, s47, 0
	s_add_i32 s84, s69, s97
	global_load_lds_dwordx4 v[210:211], off
	v_lshl_add_u64 v[212:213], s[80:81], 0, v[194:195]
	s_mov_b32 m0, s84
	v_lshl_add_u64 v[214:215], s[48:49], 0, v[196:197]
	global_load_lds_dwordx4 v[212:213], off
	v_lshl_add_u64 v[212:213], s[80:81], 0, v[198:199]
	s_add_i32 m0, s84, 0x2000
	s_nop 0
	global_load_lds_dwordx4 v[212:213], off
	v_lshl_add_u64 v[212:213], s[48:49], 0, v[192:193]
	s_mov_b32 m0, s94
	s_nop 0
	global_load_lds_dwordx4 v[212:213], off
	s_mov_b32 m0, s51
	s_nop 0
	global_load_lds_dwordx4 v[214:215], off
	s_waitcnt vmcnt(8)
	s_waitcnt lgkmcnt(0)
	s_setprio 1
	s_barrier
	v_mfma_f32_16x16x32_bf16 v[60:63], v[128:131], v[160:163], v[60:63]
	v_mfma_f32_16x16x32_bf16 v[56:59], v[136:139], v[160:163], v[56:59]
	v_mfma_f32_16x16x32_bf16 v[36:39], v[128:131], v[168:171], v[36:39]
	v_mfma_f32_16x16x32_bf16 v[32:35], v[136:139], v[168:171], v[32:35]
	v_mfma_f32_16x16x32_bf16 v[20:23], v[128:131], v[176:179], v[20:23]
	v_mfma_f32_16x16x32_bf16 v[16:19], v[136:139], v[176:179], v[16:19]
	v_mfma_f32_16x16x32_bf16 v[4:7], v[128:131], v[184:187], v[4:7]
	v_mfma_f32_16x16x32_bf16 v[0:3], v[136:139], v[184:187], v[0:3]
	v_mfma_f32_16x16x32_bf16 v[60:63], v[132:135], v[164:167], v[60:63]
	v_mfma_f32_16x16x32_bf16 v[56:59], v[140:143], v[164:167], v[56:59]
	v_mfma_f32_16x16x32_bf16 v[36:39], v[132:135], v[172:175], v[36:39]
	v_mfma_f32_16x16x32_bf16 v[32:35], v[140:143], v[172:175], v[32:35]
	v_mfma_f32_16x16x32_bf16 v[20:23], v[132:135], v[180:183], v[20:23]
	v_mfma_f32_16x16x32_bf16 v[16:19], v[140:143], v[180:183], v[16:19]
	v_mfma_f32_16x16x32_bf16 v[4:7], v[132:135], v[188:191], v[4:7]
	v_mfma_f32_16x16x32_bf16 v[0:3], v[140:143], v[188:191], v[0:3]
	v_mfma_f32_16x16x32_bf16 v[76:79], v[144:147], v[160:163], v[76:79]
	v_mfma_f32_16x16x32_bf16 v[72:75], v[152:155], v[160:163], v[72:75]
	v_mfma_f32_16x16x32_bf16 v[44:47], v[144:147], v[168:171], v[44:47]
	v_mfma_f32_16x16x32_bf16 v[40:43], v[152:155], v[168:171], v[40:43]
	v_mfma_f32_16x16x32_bf16 v[28:31], v[144:147], v[176:179], v[28:31]
	v_mfma_f32_16x16x32_bf16 v[24:27], v[152:155], v[176:179], v[24:27]
	v_mfma_f32_16x16x32_bf16 v[12:15], v[144:147], v[184:187], v[12:15]
	v_mfma_f32_16x16x32_bf16 v[8:11], v[152:155], v[184:187], v[8:11]
	v_mfma_f32_16x16x32_bf16 v[76:79], v[148:151], v[164:167], v[76:79]
	v_mfma_f32_16x16x32_bf16 v[72:75], v[156:159], v[164:167], v[72:75]
	v_mfma_f32_16x16x32_bf16 v[44:47], v[148:151], v[172:175], v[44:47]
	v_mfma_f32_16x16x32_bf16 v[40:43], v[156:159], v[172:175], v[40:43]
	v_mfma_f32_16x16x32_bf16 v[28:31], v[148:151], v[180:183], v[28:31]
	v_mfma_f32_16x16x32_bf16 v[24:27], v[156:159], v[180:183], v[24:27]
	v_mfma_f32_16x16x32_bf16 v[12:15], v[148:151], v[188:191], v[12:15]
	v_mfma_f32_16x16x32_bf16 v[8:11], v[156:159], v[188:191], v[8:11]
	s_barrier
	s_setprio 0
	s_add_i32 s80, 0, 0x18000
	s_add_i32 s81, 0, 0x1c000
	v_add_u32_e32 v140, s80, v226
	v_add_u32_e32 v156, s81, v226
	ds_read_b128 v[128:131], v140
	ds_read_b128 v[132:135], v140 offset:1024
	ds_read_b128 v[136:139], v140 offset:2048
	ds_read_b128 v[140:143], v140 offset:3072
	ds_read_b128 v[144:147], v156
	ds_read_b128 v[148:151], v156 offset:1024
	ds_read_b128 v[152:155], v156 offset:2048
	ds_read_b128 v[156:159], v156 offset:3072
	s_add_u32 s48, s48, 0x400000
	s_addc_u32 s49, s49, 0
	s_mov_b32 m0, s52
	v_lshl_add_u64 v[216:217], s[48:49], 0, v[192:193]
	ds_read_b128 v[160:163], v230 offset:32768
	ds_read_b128 v[164:167], v230 offset:33792
	ds_read_b128 v[168:171], v230 offset:34816
	ds_read_b128 v[172:175], v230 offset:35840
	ds_read_b128 v[176:179], v230 offset:36864
	ds_read_b128 v[180:183], v230 offset:37888
	ds_read_b128 v[184:187], v230 offset:38912
	ds_read_b128 v[188:191], v230 offset:39936
	global_load_lds_dwordx4 v[216:217], off
	v_lshl_add_u64 v[216:217], s[48:49], 0, v[196:197]
	s_mov_b32 m0, s53
	s_nop 0
	global_load_lds_dwordx4 v[216:217], off
	s_waitcnt vmcnt(8)
	s_waitcnt lgkmcnt(0)
	s_setprio 1
	s_barrier
	v_mfma_f32_16x16x32_bf16 v[112:115], v[128:131], v[160:163], v[112:115]
	v_mfma_f32_16x16x32_bf16 v[116:119], v[136:139], v[160:163], v[116:119]
	v_mfma_f32_16x16x32_bf16 v[100:103], v[128:131], v[168:171], v[100:103]
	v_mfma_f32_16x16x32_bf16 v[96:99], v[136:139], v[168:171], v[96:99]
	v_mfma_f32_16x16x32_bf16 v[84:87], v[128:131], v[176:179], v[84:87]
	v_mfma_f32_16x16x32_bf16 v[80:83], v[136:139], v[176:179], v[80:83]
	v_mfma_f32_16x16x32_bf16 v[52:55], v[128:131], v[184:187], v[52:55]
	v_mfma_f32_16x16x32_bf16 v[48:51], v[136:139], v[184:187], v[48:51]
	v_mfma_f32_16x16x32_bf16 v[112:115], v[132:135], v[164:167], v[112:115]
	v_mfma_f32_16x16x32_bf16 v[116:119], v[140:143], v[164:167], v[116:119]
	v_mfma_f32_16x16x32_bf16 v[100:103], v[132:135], v[172:175], v[100:103]
	v_mfma_f32_16x16x32_bf16 v[96:99], v[140:143], v[172:175], v[96:99]
	v_mfma_f32_16x16x32_bf16 v[84:87], v[132:135], v[180:183], v[84:87]
	v_mfma_f32_16x16x32_bf16 v[80:83], v[140:143], v[180:183], v[80:83]
	v_mfma_f32_16x16x32_bf16 v[52:55], v[132:135], v[188:191], v[52:55]
	v_mfma_f32_16x16x32_bf16 v[48:51], v[140:143], v[188:191], v[48:51]
	v_mfma_f32_16x16x32_bf16 v[124:127], v[144:147], v[160:163], v[124:127]
	v_mfma_f32_16x16x32_bf16 v[120:123], v[152:155], v[160:163], v[120:123]
	v_mfma_f32_16x16x32_bf16 v[108:111], v[144:147], v[168:171], v[108:111]
	v_mfma_f32_16x16x32_bf16 v[104:107], v[152:155], v[168:171], v[104:107]
	v_mfma_f32_16x16x32_bf16 v[92:95], v[144:147], v[176:179], v[92:95]
	v_mfma_f32_16x16x32_bf16 v[88:91], v[152:155], v[176:179], v[88:91]
	v_mfma_f32_16x16x32_bf16 v[68:71], v[144:147], v[184:187], v[68:71]
	v_mfma_f32_16x16x32_bf16 v[64:67], v[152:155], v[184:187], v[64:67]
	v_mfma_f32_16x16x32_bf16 v[124:127], v[148:151], v[164:167], v[124:127]
	v_mfma_f32_16x16x32_bf16 v[120:123], v[156:159], v[164:167], v[120:123]
	v_mfma_f32_16x16x32_bf16 v[108:111], v[148:151], v[172:175], v[108:111]
	v_mfma_f32_16x16x32_bf16 v[104:107], v[156:159], v[172:175], v[104:107]
	v_mfma_f32_16x16x32_bf16 v[92:95], v[148:151], v[180:183], v[92:95]
	v_mfma_f32_16x16x32_bf16 v[88:91], v[156:159], v[180:183], v[88:91]
	v_mfma_f32_16x16x32_bf16 v[68:71], v[148:151], v[188:191], v[68:71]
	v_mfma_f32_16x16x32_bf16 v[64:67], v[156:159], v[188:191], v[64:67]
	s_barrier
	s_setprio 0
	s_add_i32 s48, s80, s97
	v_lshl_add_u64 v[208:209], v[208:209], 0, s[12:13]
	s_mov_b32 m0, s48
	ds_read_b128 v[160:163], v230 offset:49152
	ds_read_b128 v[164:167], v230 offset:50176
	ds_read_b128 v[168:171], v230 offset:51200
	ds_read_b128 v[172:175], v230 offset:52224
	ds_read_b128 v[176:179], v230 offset:53248
	ds_read_b128 v[180:183], v230 offset:54272
	ds_read_b128 v[184:187], v230 offset:55296
	ds_read_b128 v[188:191], v230 offset:56320
	global_load_lds_dwordx4 v[208:209], off
	s_add_i32 m0, s48, 0x2000
	s_add_u32 s46, s46, 0x400080
	v_lshl_add_u64 v[208:209], v[210:211], 0, s[12:13]
	s_addc_u32 s47, s47, 0
	s_add_i32 s48, s81, s97
	global_load_lds_dwordx4 v[208:209], off
	v_lshl_add_u64 v[208:209], s[46:47], 0, v[194:195]
	s_mov_b32 m0, s48
	s_nop 0
	global_load_lds_dwordx4 v[208:209], off
	v_lshl_add_u64 v[208:209], s[46:47], 0, v[198:199]
	s_add_i32 m0, s48, 0x2000
	s_nop 0
	global_load_lds_dwordx4 v[208:209], off
	v_lshl_add_u64 v[208:209], v[212:213], 0, s[12:13]
	s_mov_b32 m0, s54
	s_nop 0
	global_load_lds_dwordx4 v[208:209], off
	v_lshl_add_u64 v[208:209], v[214:215], 0, s[12:13]
	s_mov_b32 m0, s55
	s_nop 0
	global_load_lds_dwordx4 v[208:209], off
	s_waitcnt vmcnt(8)
	s_waitcnt lgkmcnt(0)
	s_setprio 1
	s_barrier
	v_mfma_f32_16x16x32_bf16 v[60:63], v[128:131], v[160:163], v[60:63]
	v_mfma_f32_16x16x32_bf16 v[56:59], v[136:139], v[160:163], v[56:59]
	v_mfma_f32_16x16x32_bf16 v[36:39], v[128:131], v[168:171], v[36:39]
	v_mfma_f32_16x16x32_bf16 v[32:35], v[136:139], v[168:171], v[32:35]
	v_mfma_f32_16x16x32_bf16 v[20:23], v[128:131], v[176:179], v[20:23]
	v_mfma_f32_16x16x32_bf16 v[16:19], v[136:139], v[176:179], v[16:19]
	v_mfma_f32_16x16x32_bf16 v[4:7], v[128:131], v[184:187], v[4:7]
	v_mfma_f32_16x16x32_bf16 v[0:3], v[136:139], v[184:187], v[0:3]
	v_mfma_f32_16x16x32_bf16 v[60:63], v[132:135], v[164:167], v[60:63]
	v_mfma_f32_16x16x32_bf16 v[56:59], v[140:143], v[164:167], v[56:59]
	v_mfma_f32_16x16x32_bf16 v[36:39], v[132:135], v[172:175], v[36:39]
	v_mfma_f32_16x16x32_bf16 v[32:35], v[140:143], v[172:175], v[32:35]
	v_mfma_f32_16x16x32_bf16 v[20:23], v[132:135], v[180:183], v[20:23]
	v_mfma_f32_16x16x32_bf16 v[16:19], v[140:143], v[180:183], v[16:19]
	v_mfma_f32_16x16x32_bf16 v[4:7], v[132:135], v[188:191], v[4:7]
	v_mfma_f32_16x16x32_bf16 v[0:3], v[140:143], v[188:191], v[0:3]
	v_mfma_f32_16x16x32_bf16 v[76:79], v[144:147], v[160:163], v[76:79]
	v_mfma_f32_16x16x32_bf16 v[72:75], v[152:155], v[160:163], v[72:75]
	v_mfma_f32_16x16x32_bf16 v[44:47], v[144:147], v[168:171], v[44:47]
	v_mfma_f32_16x16x32_bf16 v[40:43], v[152:155], v[168:171], v[40:43]
	v_mfma_f32_16x16x32_bf16 v[28:31], v[144:147], v[176:179], v[28:31]
	v_mfma_f32_16x16x32_bf16 v[24:27], v[152:155], v[176:179], v[24:27]
	v_mfma_f32_16x16x32_bf16 v[12:15], v[144:147], v[184:187], v[12:15]
	v_mfma_f32_16x16x32_bf16 v[8:11], v[152:155], v[184:187], v[8:11]
	v_mfma_f32_16x16x32_bf16 v[76:79], v[148:151], v[164:167], v[76:79]
	v_mfma_f32_16x16x32_bf16 v[72:75], v[156:159], v[164:167], v[72:75]
	v_mfma_f32_16x16x32_bf16 v[44:47], v[148:151], v[172:175], v[44:47]
	v_mfma_f32_16x16x32_bf16 v[40:43], v[156:159], v[172:175], v[40:43]
	v_mfma_f32_16x16x32_bf16 v[28:31], v[148:151], v[180:183], v[28:31]
	v_mfma_f32_16x16x32_bf16 v[24:27], v[156:159], v[180:183], v[24:27]
	v_mfma_f32_16x16x32_bf16 v[12:15], v[148:151], v[188:191], v[12:15]
	v_mfma_f32_16x16x32_bf16 v[8:11], v[156:159], v[188:191], v[8:11]
	s_barrier
	s_setprio 0
	s_add_u32 s77, s77, 0x100
	s_addc_u32 s78, s78, 0
	s_add_u32 s44, s44, 0x100
	s_addc_u32 s45, s45, 0
	s_cmp_ge_u32 s79, s76
	s_mov_b32 s46, s79
	s_cbranch_scc0 .LBB0_2453
	v_readlane_b32 s44, v254, 27
	v_readlane_b32 s45, v254, 28
	s_and_b64 vcc, exec, s[44:45]
	s_cbranch_vccz .LBB0_2461
	s_barrier
	s_cmp_lt_i32 s10, 0
	s_mov_b64 s[44:45], -1
	s_cbranch_scc1 .LBB0_2462
